# on top of v18: in-projection epilogue stores use sc1 (write-through) so the following grid barrier's L2 write-back has less dirty data on its critical path
# speedup vs baseline: 1.0083x; 1.0083x over previous
; __device__ __forceinline__ unsigned cvt_pk_bf16(float lo, float hi) { unsigned r; asm volatile("v_cvt_pk_bf16_f32 %0, %1, %2" : "=v"(r) : "v"(lo), "v"(hi)); return r; }
; #define GAS __attribute__((address_space(1)))
; __device__ __forceinline__ float silu_f(float x) { return x * __builtin_amdgcn_rcpf(1.f + __builtin_amdgcn_exp2f(x * -1.4426950408889634f)); }
;     __device__ __forceinline__ void operator()(const pg8::f32x4 (&acc)[2][2][4][2], const pg8::Unit& u, int wr, int wc, int fr, int fq) const {
;     ...
;             for (int m = 0; m < 4; ++m) { GAS pg8::bf16_t* rowp = O + (size_t)(row0 + ai * 128 + m * 16) * PW + col0;
; #pragma unroll
;                 for (int bj = 0; bj < 2; ++bj) { pg8::f32x4 v0 = acc[ai][bj][m][0] * rsr[ai][m], v1 = acc[ai][bj][m][1] * rsr[ai][m];
;                     if (act == 1) {
; #pragma unroll
;                         for (int e = 0; e < 4; ++e) { v0[e] = silu_f(v0[e]); v1[e] = silu_f(v1[e]); } }
;                     else if (act == 2) {
; #pragma unroll
;                         for (int e = 0; e < 4; ++e) { const float s0 = __builtin_amdgcn_rcpf(1.f + __builtin_amdgcn_exp2f(v0[e] * -1.4426950408889634f)), s1 = __builtin_amdgcn_rcpf(1.f + __builtin_amdgcn_exp2f(v1[e] * -1.4426950408889634f));
;                             v0[e] = __builtin_amdgcn_logf(lbv[bj][0][e] + (1.f - lbv[bj][0][e]) * s0); v1[e] = __builtin_amdgcn_logf(lbv[bj][1][e] + (1.f - lbv[bj][1][e]) * s1);     } }
;                     pg8::u32x4 w; w.x = pg8::cvt_pk_bf16(v0[0], v0[1]); w.y = pg8::cvt_pk_bf16(v0[2], v0[3]); w.z = pg8::cvt_pk_bf16(v1[0], v1[1]); w.w = pg8::cvt_pk_bf16(v1[2], v1[3]);
;                     *(GAS pg8::u32x4*)(rowp + bj * 128) = w; } }
.LBB0_103:
	v_ashrrev_i32_e32 v167, 31, v166
	v_lshlrev_b64 v[172:173], 14, v[166:167]
	v_lshl_add_u64 v[172:173], s[12:13], 0, v[172:173]
	v_lshl_add_u64 v[172:173], v[170:171], 1, v[172:173]
	v_cvt_pk_bf16_f32 v174, v112, v196
	v_cvt_pk_bf16_f32 v175, v198, v203
	v_cvt_pk_bf16_f32 v176, v195, v197
	v_cvt_pk_bf16_f32 v177, v199, v202
	v_mov_b32_e32 v180, v168
	v_mov_b32_e32 v181, v168
	v_mov_b32_e32 v178, v168
	v_mov_b32_e32 v179, v168
	global_store_dwordx4 v[172:173], v[174:177], off sc1
	s_mov_b64 s[0:1], -1
	s_cmp_gt_i32 s23, 1
	v_pk_mul_f32 v[174:175], v[120:121], v[178:179]
	v_pk_mul_f32 v[176:177], v[118:119], v[180:181]
	v_pk_mul_f32 v[178:179], v[116:117], v[178:179]
	v_pk_mul_f32 v[180:181], v[114:115], v[180:181]
	v_sub_f32_e32 v203, 1.0, v134
	v_sub_f32_e32 v202, 1.0, v130
	v_sub_f32_e32 v199, 1.0, v135
	v_sub_f32_e32 v198, 1.0, v131
	v_sub_f32_e32 v197, 1.0, v136
	v_sub_f32_e32 v196, 1.0, v132
	v_sub_f32_e32 v195, 1.0, v137
	v_sub_f32_e32 v112, 1.0, v133
	s_cbranch_scc0 .LBB0_105
	v_mul_f32_e32 v216, 0xbfb8aa3b, v175
	v_mul_f32_e32 v210, 0xbfb8aa3b, v176
	v_mul_f32_e32 v211, 0xbfb8aa3b, v180
	v_mul_f32_e32 v212, 0xbfb8aa3b, v177
	v_mul_f32_e32 v213, 0xbfb8aa3b, v181
	v_mul_f32_e32 v214, 0xbfb8aa3b, v174
	v_mul_f32_e32 v215, 0xbfb8aa3b, v178
	v_exp_f32_e32 v216, v216
	v_mul_f32_e32 v217, 0xbfb8aa3b, v179
	v_exp_f32_e32 v210, v210
	v_exp_f32_e32 v211, v211
	v_exp_f32_e32 v212, v212
	v_exp_f32_e32 v213, v213
	v_exp_f32_e32 v214, v214
	v_exp_f32_e32 v215, v215
	v_exp_f32_e32 v217, v217
	v_add_f32_e32 v216, 1.0, v216
	v_add_f32_e32 v210, 1.0, v210
	v_add_f32_e32 v211, 1.0, v211
	v_add_f32_e32 v212, 1.0, v212
	v_add_f32_e32 v213, 1.0, v213
	v_add_f32_e32 v214, 1.0, v214
	v_add_f32_e32 v215, 1.0, v215
	v_rcp_f32_e32 v216, v216
	v_add_f32_e32 v217, 1.0, v217
	v_rcp_f32_e32 v210, v210
	v_rcp_f32_e32 v211, v211
	v_rcp_f32_e32 v212, v212
	v_rcp_f32_e32 v213, v213
	v_rcp_f32_e32 v214, v214
	v_rcp_f32_e32 v215, v215
	v_rcp_f32_e32 v218, v217
	v_fma_f32 v216, v216, v195, v137
	v_fma_f32 v210, v210, v203, v134
	v_fma_f32 v211, v211, v202, v130
	v_fma_f32 v212, v212, v199, v135
	v_fma_f32 v213, v213, v198, v131
	v_fma_f32 v214, v214, v197, v136
	v_fma_f32 v215, v215, v196, v132
	v_log_f32_e32 v217, v216
	v_fma_f32 v216, v218, v112, v133
	v_log_f32_e32 v210, v210
	v_log_f32_e32 v211, v211
	v_log_f32_e32 v212, v212
	v_log_f32_e32 v213, v213
	v_log_f32_e32 v214, v214
	v_log_f32_e32 v215, v215
	v_log_f32_e32 v216, v216
	s_mov_b64 s[0:1], 0

; __device__ __forceinline__ unsigned cvt_pk_bf16(float lo, float hi) { unsigned r; asm volatile("v_cvt_pk_bf16_f32 %0, %1, %2" : "=v"(r) : "v"(lo), "v"(hi)); return r; }
; #define GAS __attribute__((address_space(1)))
; __device__ __forceinline__ float silu_f(float x) { return x * __builtin_amdgcn_rcpf(1.f + __builtin_amdgcn_exp2f(x * -1.4426950408889634f)); }
;     __device__ __forceinline__ void operator()(const pg8::f32x4 (&acc)[2][2][4][2], const pg8::Unit& u, int wr, int wc, int fr, int fq) const {
;     ...
;             for (int m = 0; m < 4; ++m) { GAS pg8::bf16_t* rowp = O + (size_t)(row0 + ai * 128 + m * 16) * PW + col0;
; #pragma unroll
;                 for (int bj = 0; bj < 2; ++bj) { pg8::f32x4 v0 = acc[ai][bj][m][0] * rsr[ai][m], v1 = acc[ai][bj][m][1] * rsr[ai][m];
;                     if (act == 1) {
; #pragma unroll
;                         for (int e = 0; e < 4; ++e) { v0[e] = silu_f(v0[e]); v1[e] = silu_f(v1[e]); } }
;                     else if (act == 2) {
; #pragma unroll
;                         for (int e = 0; e < 4; ++e) { const float s0 = __builtin_amdgcn_rcpf(1.f + __builtin_amdgcn_exp2f(v0[e] * -1.4426950408889634f)), s1 = __builtin_amdgcn_rcpf(1.f + __builtin_amdgcn_exp2f(v1[e] * -1.4426950408889634f));
;                             v0[e] = __builtin_amdgcn_logf(lbv[bj][0][e] + (1.f - lbv[bj][0][e]) * s0); v1[e] = __builtin_amdgcn_logf(lbv[bj][1][e] + (1.f - lbv[bj][1][e]) * s1);     } }
;                     pg8::u32x4 w; w.x = pg8::cvt_pk_bf16(v0[0], v0[1]); w.y = pg8::cvt_pk_bf16(v0[2], v0[3]); w.z = pg8::cvt_pk_bf16(v1[0], v1[1]); w.w = pg8::cvt_pk_bf16(v1[2], v1[3]);
;                     *(GAS pg8::u32x4*)(rowp + bj * 128) = w; } }
.LBB0_109:
	v_cvt_pk_bf16_f32 v174, v210, v212
	v_cvt_pk_bf16_f32 v175, v214, v217
	v_cvt_pk_bf16_f32 v176, v211, v213
	v_cvt_pk_bf16_f32 v177, v215, v216
	v_mov_b32_e32 v178, v169
	global_store_dwordx4 v[172:173], v[174:177], off offset:256 sc1
	v_pk_mul_f32 v[172:173], v[110:111], v[178:179] op_sel_hi:[1,0]
	s_cmp_gt_i32 s23, 1
	v_pk_mul_f32 v[174:175], v[108:109], v[178:179] op_sel_hi:[1,0]
	v_pk_mul_f32 v[176:177], v[106:107], v[178:179] op_sel_hi:[1,0]
	v_pk_mul_f32 v[178:179], v[104:105], v[178:179] op_sel_hi:[1,0]
	s_mov_b64 s[0:1], -1
	s_cbranch_scc0 .LBB0_111
	v_mul_f32_e32 v180, 0xbfb8aa3b, v174
	v_exp_f32_e32 v180, v180
	v_mul_f32_e32 v181, 0xbfb8aa3b, v178
	v_exp_f32_e32 v181, v181
	v_mul_f32_e32 v210, 0xbfb8aa3b, v175
	v_add_f32_e32 v180, 1.0, v180
	v_rcp_f32_e32 v180, v180
	v_add_f32_e32 v181, 1.0, v181
	v_rcp_f32_e32 v181, v181
	v_exp_f32_e32 v211, v210
	v_fma_f32 v180, v180, v209, v142
	v_log_f32_e32 v210, v180
	v_fma_f32 v180, v181, v208, v138
	v_mul_f32_e32 v181, 0xbfb8aa3b, v179
	v_add_f32_e32 v211, 1.0, v211
	v_exp_f32_e32 v181, v181
	v_rcp_f32_e32 v212, v211
	v_log_f32_e32 v211, v180
	v_mul_f32_e32 v213, 0xbfb8aa3b, v176
	v_add_f32_e32 v180, 1.0, v181
	v_fma_f32 v181, v212, v207, v143
	v_log_f32_e32 v212, v181
	v_mul_f32_e32 v181, 0xbfb8aa3b, v172
	v_exp_f32_e32 v181, v181
	v_rcp_f32_e32 v180, v180
	v_exp_f32_e32 v214, v213
	v_mul_f32_e32 v215, 0xbfb8aa3b, v177
	v_add_f32_e32 v181, 1.0, v181
	v_rcp_f32_e32 v181, v181
	v_fma_f32 v180, v180, v206, v139
	v_log_f32_e32 v213, v180
	v_add_f32_e32 v180, 1.0, v214
	v_fma_f32 v181, v181, v205, v144
	v_log_f32_e32 v214, v181
	v_mul_f32_e32 v181, 0xbfb8aa3b, v173
	v_exp_f32_e32 v181, v181
	v_exp_f32_e32 v215, v215
	v_rcp_f32_e32 v180, v180
	s_mov_b64 s[0:1], 0
	v_add_f32_e32 v181, 1.0, v181
	v_rcp_f32_e32 v181, v181
	v_add_f32_e32 v215, 1.0, v215
	v_rcp_f32_e32 v216, v215
	v_fma_f32 v180, v180, v204, v140
	v_log_f32_e32 v215, v180
	v_fma_f32 v180, v181, v201, v145
	v_log_f32_e32 v217, v180
	v_fma_f32 v180, v216, v200, v141
	v_log_f32_e32 v216, v180

; __device__ __forceinline__ unsigned cvt_pk_bf16(float lo, float hi) { unsigned r; asm volatile("v_cvt_pk_bf16_f32 %0, %1, %2" : "=v"(r) : "v"(lo), "v"(hi)); return r; }
; #define GAS __attribute__((address_space(1)))
; __device__ __forceinline__ float silu_f(float x) { return x * __builtin_amdgcn_rcpf(1.f + __builtin_amdgcn_exp2f(x * -1.4426950408889634f)); }
;     __device__ __forceinline__ void operator()(const pg8::f32x4 (&acc)[2][2][4][2], const pg8::Unit& u, int wr, int wc, int fr, int fq) const {
;     ...
;             for (int m = 0; m < 4; ++m) { GAS pg8::bf16_t* rowp = O + (size_t)(row0 + ai * 128 + m * 16) * PW + col0;
; #pragma unroll
;                 for (int bj = 0; bj < 2; ++bj) { pg8::f32x4 v0 = acc[ai][bj][m][0] * rsr[ai][m], v1 = acc[ai][bj][m][1] * rsr[ai][m];
;                     if (act == 1) {
; #pragma unroll
;                         for (int e = 0; e < 4; ++e) { v0[e] = silu_f(v0[e]); v1[e] = silu_f(v1[e]); } }
;                     else if (act == 2) {
; #pragma unroll
;                         for (int e = 0; e < 4; ++e) { const float s0 = __builtin_amdgcn_rcpf(1.f + __builtin_amdgcn_exp2f(v0[e] * -1.4426950408889634f)), s1 = __builtin_amdgcn_rcpf(1.f + __builtin_amdgcn_exp2f(v1[e] * -1.4426950408889634f));
;                             v0[e] = __builtin_amdgcn_logf(lbv[bj][0][e] + (1.f - lbv[bj][0][e]) * s0); v1[e] = __builtin_amdgcn_logf(lbv[bj][1][e] + (1.f - lbv[bj][1][e]) * s1);     } }
;                     pg8::u32x4 w; w.x = pg8::cvt_pk_bf16(v0[0], v0[1]); w.y = pg8::cvt_pk_bf16(v0[2], v0[3]); w.z = pg8::cvt_pk_bf16(v1[0], v1[1]); w.w = pg8::cvt_pk_bf16(v1[2], v1[3]);
;                     *(GAS pg8::u32x4*)(rowp + bj * 128) = w; } }
.LBB0_115:
	v_or_b32_e32 v172, 16, v166
	v_ashrrev_i32_e32 v173, 31, v172
	v_lshlrev_b64 v[172:173], 14, v[172:173]
	v_lshl_add_u64 v[172:173], s[12:13], 0, v[172:173]
	v_lshl_add_u64 v[172:173], v[170:171], 1, v[172:173]
	v_cvt_pk_bf16_f32 v174, v210, v212
	v_cvt_pk_bf16_f32 v175, v214, v217
	v_cvt_pk_bf16_f32 v176, v211, v213
	v_cvt_pk_bf16_f32 v177, v215, v216
	v_mov_b32_e32 v180, v169
	v_mov_b32_e32 v181, v169
	v_mov_b32_e32 v178, v169
	v_mov_b32_e32 v179, v169
	global_store_dwordx4 v[172:173], v[174:177], off sc1
	s_cmp_gt_i32 s23, 1
	s_mov_b64 s[0:1], -1
	v_pk_mul_f32 v[174:175], v[102:103], v[178:179]
	v_pk_mul_f32 v[176:177], v[100:101], v[180:181]
	v_pk_mul_f32 v[178:179], v[98:99], v[178:179]
	v_pk_mul_f32 v[180:181], v[96:97], v[180:181]
	s_cbranch_scc0 .LBB0_117
	v_mul_f32_e32 v216, 0xbfb8aa3b, v175
	v_mul_f32_e32 v210, 0xbfb8aa3b, v176
	v_mul_f32_e32 v211, 0xbfb8aa3b, v180
	v_mul_f32_e32 v212, 0xbfb8aa3b, v177
	v_mul_f32_e32 v213, 0xbfb8aa3b, v181
	v_mul_f32_e32 v214, 0xbfb8aa3b, v174
	v_mul_f32_e32 v215, 0xbfb8aa3b, v178
	v_exp_f32_e32 v216, v216
	v_mul_f32_e32 v217, 0xbfb8aa3b, v179
	v_exp_f32_e32 v210, v210
	v_exp_f32_e32 v211, v211
	v_exp_f32_e32 v212, v212
	v_exp_f32_e32 v213, v213
	v_exp_f32_e32 v214, v214
	v_exp_f32_e32 v215, v215
	v_exp_f32_e32 v217, v217
	v_add_f32_e32 v216, 1.0, v216
	v_add_f32_e32 v210, 1.0, v210
	v_add_f32_e32 v211, 1.0, v211
	v_add_f32_e32 v212, 1.0, v212
	v_add_f32_e32 v213, 1.0, v213
	v_add_f32_e32 v214, 1.0, v214
	v_add_f32_e32 v215, 1.0, v215
	v_rcp_f32_e32 v216, v216
	v_add_f32_e32 v217, 1.0, v217
	v_rcp_f32_e32 v210, v210
	v_rcp_f32_e32 v211, v211
	v_rcp_f32_e32 v212, v212
	v_rcp_f32_e32 v213, v213
	v_rcp_f32_e32 v214, v214
	v_rcp_f32_e32 v215, v215
	v_rcp_f32_e32 v218, v217
	v_fma_f32 v216, v216, v195, v137
	v_fma_f32 v210, v210, v203, v134
	v_fma_f32 v211, v211, v202, v130
	v_fma_f32 v212, v212, v199, v135
	v_fma_f32 v213, v213, v198, v131
	v_fma_f32 v214, v214, v197, v136
	v_fma_f32 v215, v215, v196, v132
	v_log_f32_e32 v217, v216
	v_fma_f32 v216, v218, v112, v133
	v_log_f32_e32 v210, v210
	v_log_f32_e32 v211, v211
	v_log_f32_e32 v212, v212
	v_log_f32_e32 v213, v213
	v_log_f32_e32 v214, v214
	v_log_f32_e32 v215, v215
	v_log_f32_e32 v216, v216
	s_mov_b64 s[0:1], 0

; __device__ __forceinline__ unsigned cvt_pk_bf16(float lo, float hi) { unsigned r; asm volatile("v_cvt_pk_bf16_f32 %0, %1, %2" : "=v"(r) : "v"(lo), "v"(hi)); return r; }
; #define GAS __attribute__((address_space(1)))
; __device__ __forceinline__ float silu_f(float x) { return x * __builtin_amdgcn_rcpf(1.f + __builtin_amdgcn_exp2f(x * -1.4426950408889634f)); }
;     __device__ __forceinline__ void operator()(const pg8::f32x4 (&acc)[2][2][4][2], const pg8::Unit& u, int wr, int wc, int fr, int fq) const {
;     ...
;             for (int m = 0; m < 4; ++m) { GAS pg8::bf16_t* rowp = O + (size_t)(row0 + ai * 128 + m * 16) * PW + col0;
; #pragma unroll
;                 for (int bj = 0; bj < 2; ++bj) { pg8::f32x4 v0 = acc[ai][bj][m][0] * rsr[ai][m], v1 = acc[ai][bj][m][1] * rsr[ai][m];
;                     if (act == 1) {
; #pragma unroll
;                         for (int e = 0; e < 4; ++e) { v0[e] = silu_f(v0[e]); v1[e] = silu_f(v1[e]); } }
;                     else if (act == 2) {
; #pragma unroll
;                         for (int e = 0; e < 4; ++e) { const float s0 = __builtin_amdgcn_rcpf(1.f + __builtin_amdgcn_exp2f(v0[e] * -1.4426950408889634f)), s1 = __builtin_amdgcn_rcpf(1.f + __builtin_amdgcn_exp2f(v1[e] * -1.4426950408889634f));
;                             v0[e] = __builtin_amdgcn_logf(lbv[bj][0][e] + (1.f - lbv[bj][0][e]) * s0); v1[e] = __builtin_amdgcn_logf(lbv[bj][1][e] + (1.f - lbv[bj][1][e]) * s1);     } }
;                     pg8::u32x4 w; w.x = pg8::cvt_pk_bf16(v0[0], v0[1]); w.y = pg8::cvt_pk_bf16(v0[2], v0[3]); w.z = pg8::cvt_pk_bf16(v1[0], v1[1]); w.w = pg8::cvt_pk_bf16(v1[2], v1[3]);
;                     *(GAS pg8::u32x4*)(rowp + bj * 128) = w; } }
.LBB0_121:
	v_cvt_pk_bf16_f32 v174, v210, v212
	v_cvt_pk_bf16_f32 v175, v214, v217
	v_cvt_pk_bf16_f32 v176, v211, v213
	v_cvt_pk_bf16_f32 v177, v215, v216
	global_store_dwordx4 v[172:173], v[174:177], off offset:256 sc1
	v_pk_mul_f32 v[172:173], v[94:95], v[164:165] op_sel_hi:[1,0]
	v_pk_mul_f32 v[178:179], v[88:89], v[164:165] op_sel_hi:[1,0]
	v_pk_mul_f32 v[174:175], v[92:93], v[164:165] op_sel_hi:[1,0]
	v_pk_mul_f32 v[176:177], v[90:91], v[164:165] op_sel_hi:[1,0]
	s_cmp_gt_i32 s23, 1
	s_mov_b64 s[0:1], -1
	s_cbranch_scc0 .LBB0_123
	v_mul_f32_e32 v180, 0xbfb8aa3b, v174
	v_exp_f32_e32 v180, v180
	v_mul_f32_e32 v181, 0xbfb8aa3b, v178
	v_exp_f32_e32 v181, v181
	v_mul_f32_e32 v210, 0xbfb8aa3b, v175
	v_add_f32_e32 v180, 1.0, v180
	v_rcp_f32_e32 v180, v180
	v_add_f32_e32 v181, 1.0, v181
	v_rcp_f32_e32 v181, v181
	v_exp_f32_e32 v211, v210
	v_fma_f32 v180, v180, v209, v142
	v_log_f32_e32 v210, v180
	v_fma_f32 v180, v181, v208, v138
	v_mul_f32_e32 v181, 0xbfb8aa3b, v179
	v_add_f32_e32 v211, 1.0, v211
	v_exp_f32_e32 v181, v181
	v_rcp_f32_e32 v212, v211
	v_log_f32_e32 v211, v180
	v_mul_f32_e32 v213, 0xbfb8aa3b, v176
	v_add_f32_e32 v180, 1.0, v181
	v_fma_f32 v181, v212, v207, v143
	v_log_f32_e32 v212, v181
	v_mul_f32_e32 v181, 0xbfb8aa3b, v172
	v_exp_f32_e32 v181, v181
	v_rcp_f32_e32 v180, v180
	v_exp_f32_e32 v214, v213
	v_mul_f32_e32 v215, 0xbfb8aa3b, v177
	v_add_f32_e32 v181, 1.0, v181
	v_rcp_f32_e32 v181, v181
	v_fma_f32 v180, v180, v206, v139
	v_log_f32_e32 v213, v180
	v_add_f32_e32 v180, 1.0, v214
	v_fma_f32 v181, v181, v205, v144
	v_log_f32_e32 v214, v181
	v_mul_f32_e32 v181, 0xbfb8aa3b, v173
	v_exp_f32_e32 v181, v181
	v_exp_f32_e32 v215, v215
	v_rcp_f32_e32 v180, v180
	s_mov_b64 s[0:1], 0
	v_add_f32_e32 v181, 1.0, v181
	v_rcp_f32_e32 v181, v181
	v_add_f32_e32 v215, 1.0, v215
	v_rcp_f32_e32 v216, v215
	v_fma_f32 v180, v180, v204, v140
	v_log_f32_e32 v215, v180
	v_fma_f32 v180, v181, v201, v145
	v_log_f32_e32 v217, v180
	v_fma_f32 v180, v216, v200, v141
	v_log_f32_e32 v216, v180

; __device__ __forceinline__ unsigned cvt_pk_bf16(float lo, float hi) { unsigned r; asm volatile("v_cvt_pk_bf16_f32 %0, %1, %2" : "=v"(r) : "v"(lo), "v"(hi)); return r; }
; #define GAS __attribute__((address_space(1)))
; __device__ __forceinline__ float silu_f(float x) { return x * __builtin_amdgcn_rcpf(1.f + __builtin_amdgcn_exp2f(x * -1.4426950408889634f)); }
;     __device__ __forceinline__ void operator()(const pg8::f32x4 (&acc)[2][2][4][2], const pg8::Unit& u, int wr, int wc, int fr, int fq) const {
;     ...
;             for (int m = 0; m < 4; ++m) { GAS pg8::bf16_t* rowp = O + (size_t)(row0 + ai * 128 + m * 16) * PW + col0;
; #pragma unroll
;                 for (int bj = 0; bj < 2; ++bj) { pg8::f32x4 v0 = acc[ai][bj][m][0] * rsr[ai][m], v1 = acc[ai][bj][m][1] * rsr[ai][m];
;                     if (act == 1) {
; #pragma unroll
;                         for (int e = 0; e < 4; ++e) { v0[e] = silu_f(v0[e]); v1[e] = silu_f(v1[e]); } }
;                     else if (act == 2) {
; #pragma unroll
;                         for (int e = 0; e < 4; ++e) { const float s0 = __builtin_amdgcn_rcpf(1.f + __builtin_amdgcn_exp2f(v0[e] * -1.4426950408889634f)), s1 = __builtin_amdgcn_rcpf(1.f + __builtin_amdgcn_exp2f(v1[e] * -1.4426950408889634f));
;                             v0[e] = __builtin_amdgcn_logf(lbv[bj][0][e] + (1.f - lbv[bj][0][e]) * s0); v1[e] = __builtin_amdgcn_logf(lbv[bj][1][e] + (1.f - lbv[bj][1][e]) * s1);     } }
;                     pg8::u32x4 w; w.x = pg8::cvt_pk_bf16(v0[0], v0[1]); w.y = pg8::cvt_pk_bf16(v0[2], v0[3]); w.z = pg8::cvt_pk_bf16(v1[0], v1[1]); w.w = pg8::cvt_pk_bf16(v1[2], v1[3]);
;                     *(GAS pg8::u32x4*)(rowp + bj * 128) = w; } }
.LBB0_127:
	v_or_b32_e32 v172, 32, v166
	v_ashrrev_i32_e32 v173, 31, v172
	v_lshlrev_b64 v[172:173], 14, v[172:173]
	v_lshl_add_u64 v[172:173], s[12:13], 0, v[172:173]
	v_lshl_add_u64 v[172:173], v[170:171], 1, v[172:173]
	v_cvt_pk_bf16_f32 v174, v210, v212
	v_cvt_pk_bf16_f32 v175, v214, v217
	v_cvt_pk_bf16_f32 v176, v211, v213
	v_cvt_pk_bf16_f32 v177, v215, v216
	v_mov_b32_e32 v180, v164
	v_mov_b32_e32 v181, v164
	v_mov_b32_e32 v178, v164
	v_mov_b32_e32 v179, v164
	global_store_dwordx4 v[172:173], v[174:177], off sc1
	s_cmp_gt_i32 s23, 1
	s_mov_b64 s[0:1], -1
	v_pk_mul_f32 v[174:175], v[86:87], v[178:179]
	v_pk_mul_f32 v[176:177], v[84:85], v[180:181]
	v_pk_mul_f32 v[178:179], v[82:83], v[178:179]
	v_pk_mul_f32 v[180:181], v[80:81], v[180:181]
	s_cbranch_scc0 .LBB0_129
	v_mul_f32_e32 v216, 0xbfb8aa3b, v175
	v_mul_f32_e32 v210, 0xbfb8aa3b, v176
	v_mul_f32_e32 v211, 0xbfb8aa3b, v180
	v_mul_f32_e32 v212, 0xbfb8aa3b, v177
	v_mul_f32_e32 v213, 0xbfb8aa3b, v181
	v_mul_f32_e32 v214, 0xbfb8aa3b, v174
	v_mul_f32_e32 v215, 0xbfb8aa3b, v178
	v_exp_f32_e32 v216, v216
	v_mul_f32_e32 v217, 0xbfb8aa3b, v179
	v_exp_f32_e32 v210, v210
	v_exp_f32_e32 v211, v211
	v_exp_f32_e32 v212, v212
	v_exp_f32_e32 v213, v213
	v_exp_f32_e32 v214, v214
	v_exp_f32_e32 v215, v215
	v_exp_f32_e32 v217, v217
	v_add_f32_e32 v216, 1.0, v216
	v_add_f32_e32 v210, 1.0, v210
	v_add_f32_e32 v211, 1.0, v211
	v_add_f32_e32 v212, 1.0, v212
	v_add_f32_e32 v213, 1.0, v213
	v_add_f32_e32 v214, 1.0, v214
	v_add_f32_e32 v215, 1.0, v215
	v_rcp_f32_e32 v216, v216
	v_add_f32_e32 v217, 1.0, v217
	v_rcp_f32_e32 v210, v210
	v_rcp_f32_e32 v211, v211
	v_rcp_f32_e32 v212, v212
	v_rcp_f32_e32 v213, v213
	v_rcp_f32_e32 v214, v214
	v_rcp_f32_e32 v215, v215
	v_rcp_f32_e32 v218, v217
	v_fma_f32 v216, v216, v195, v137
	v_fma_f32 v210, v210, v203, v134
	v_fma_f32 v211, v211, v202, v130
	v_fma_f32 v212, v212, v199, v135
	v_fma_f32 v213, v213, v198, v131
	v_fma_f32 v214, v214, v197, v136
	v_fma_f32 v215, v215, v196, v132
	v_log_f32_e32 v217, v216
	v_fma_f32 v216, v218, v112, v133
	v_log_f32_e32 v210, v210
	v_log_f32_e32 v211, v211
	v_log_f32_e32 v212, v212
	v_log_f32_e32 v213, v213
	v_log_f32_e32 v214, v214
	v_log_f32_e32 v215, v215
	v_log_f32_e32 v216, v216
	s_mov_b64 s[0:1], 0

; __device__ __forceinline__ unsigned cvt_pk_bf16(float lo, float hi) { unsigned r; asm volatile("v_cvt_pk_bf16_f32 %0, %1, %2" : "=v"(r) : "v"(lo), "v"(hi)); return r; }
; #define GAS __attribute__((address_space(1)))
; __device__ __forceinline__ float silu_f(float x) { return x * __builtin_amdgcn_rcpf(1.f + __builtin_amdgcn_exp2f(x * -1.4426950408889634f)); }
;     __device__ __forceinline__ void operator()(const pg8::f32x4 (&acc)[2][2][4][2], const pg8::Unit& u, int wr, int wc, int fr, int fq) const {
;     ...
;             for (int m = 0; m < 4; ++m) { GAS pg8::bf16_t* rowp = O + (size_t)(row0 + ai * 128 + m * 16) * PW + col0;
; #pragma unroll
;                 for (int bj = 0; bj < 2; ++bj) { pg8::f32x4 v0 = acc[ai][bj][m][0] * rsr[ai][m], v1 = acc[ai][bj][m][1] * rsr[ai][m];
;                     if (act == 1) {
; #pragma unroll
;                         for (int e = 0; e < 4; ++e) { v0[e] = silu_f(v0[e]); v1[e] = silu_f(v1[e]); } }
;                     else if (act == 2) {
; #pragma unroll
;                         for (int e = 0; e < 4; ++e) { const float s0 = __builtin_amdgcn_rcpf(1.f + __builtin_amdgcn_exp2f(v0[e] * -1.4426950408889634f)), s1 = __builtin_amdgcn_rcpf(1.f + __builtin_amdgcn_exp2f(v1[e] * -1.4426950408889634f));
;                             v0[e] = __builtin_amdgcn_logf(lbv[bj][0][e] + (1.f - lbv[bj][0][e]) * s0); v1[e] = __builtin_amdgcn_logf(lbv[bj][1][e] + (1.f - lbv[bj][1][e]) * s1);     } }
;                     pg8::u32x4 w; w.x = pg8::cvt_pk_bf16(v0[0], v0[1]); w.y = pg8::cvt_pk_bf16(v0[2], v0[3]); w.z = pg8::cvt_pk_bf16(v1[0], v1[1]); w.w = pg8::cvt_pk_bf16(v1[2], v1[3]);
;                     *(GAS pg8::u32x4*)(rowp + bj * 128) = w; } }
.LBB0_133:
	v_cvt_pk_bf16_f32 v174, v210, v212
	v_cvt_pk_bf16_f32 v175, v214, v217
	v_cvt_pk_bf16_f32 v176, v211, v213
	v_cvt_pk_bf16_f32 v177, v215, v216
	v_mov_b32_e32 v178, v165
	global_store_dwordx4 v[172:173], v[174:177], off offset:256 sc1
	v_pk_mul_f32 v[172:173], v[78:79], v[178:179] op_sel_hi:[1,0]
	s_cmp_gt_i32 s23, 1
	v_pk_mul_f32 v[174:175], v[76:77], v[178:179] op_sel_hi:[1,0]
	v_pk_mul_f32 v[176:177], v[74:75], v[178:179] op_sel_hi:[1,0]
	v_pk_mul_f32 v[178:179], v[72:73], v[178:179] op_sel_hi:[1,0]
	s_mov_b64 s[0:1], -1
	s_cbranch_scc0 .LBB0_135
	v_mul_f32_e32 v180, 0xbfb8aa3b, v174
	v_exp_f32_e32 v180, v180
	v_mul_f32_e32 v181, 0xbfb8aa3b, v178
	v_exp_f32_e32 v181, v181
	v_mul_f32_e32 v210, 0xbfb8aa3b, v175
	v_add_f32_e32 v180, 1.0, v180
	v_rcp_f32_e32 v180, v180
	v_add_f32_e32 v181, 1.0, v181
	v_rcp_f32_e32 v181, v181
	v_exp_f32_e32 v211, v210
	v_fma_f32 v180, v180, v209, v142
	v_log_f32_e32 v210, v180
	v_fma_f32 v180, v181, v208, v138
	v_mul_f32_e32 v181, 0xbfb8aa3b, v179
	v_add_f32_e32 v211, 1.0, v211
	v_exp_f32_e32 v181, v181
	v_rcp_f32_e32 v212, v211
	v_log_f32_e32 v211, v180
	v_mul_f32_e32 v213, 0xbfb8aa3b, v176
	v_add_f32_e32 v180, 1.0, v181
	v_fma_f32 v181, v212, v207, v143
	v_log_f32_e32 v212, v181
	v_mul_f32_e32 v181, 0xbfb8aa3b, v172
	v_exp_f32_e32 v181, v181
	v_rcp_f32_e32 v180, v180
	v_exp_f32_e32 v214, v213
	v_mul_f32_e32 v215, 0xbfb8aa3b, v177
	v_add_f32_e32 v181, 1.0, v181
	v_rcp_f32_e32 v181, v181
	v_fma_f32 v180, v180, v206, v139
	v_log_f32_e32 v213, v180
	v_add_f32_e32 v180, 1.0, v214
	v_fma_f32 v181, v181, v205, v144
	v_log_f32_e32 v214, v181
	v_mul_f32_e32 v181, 0xbfb8aa3b, v173
	v_exp_f32_e32 v181, v181
	v_exp_f32_e32 v215, v215
	v_rcp_f32_e32 v180, v180
	s_mov_b64 s[0:1], 0
	v_add_f32_e32 v181, 1.0, v181
	v_rcp_f32_e32 v181, v181
	v_add_f32_e32 v215, 1.0, v215
	v_rcp_f32_e32 v216, v215
	v_fma_f32 v180, v180, v204, v140
	v_log_f32_e32 v215, v180
	v_fma_f32 v180, v181, v201, v145
	v_log_f32_e32 v217, v180
	v_fma_f32 v180, v216, v200, v141
	v_log_f32_e32 v216, v180

; __device__ __forceinline__ unsigned cvt_pk_bf16(float lo, float hi) { unsigned r; asm volatile("v_cvt_pk_bf16_f32 %0, %1, %2" : "=v"(r) : "v"(lo), "v"(hi)); return r; }
; #define GAS __attribute__((address_space(1)))
; __device__ __forceinline__ float silu_f(float x) { return x * __builtin_amdgcn_rcpf(1.f + __builtin_amdgcn_exp2f(x * -1.4426950408889634f)); }
;     __device__ __forceinline__ void operator()(const pg8::f32x4 (&acc)[2][2][4][2], const pg8::Unit& u, int wr, int wc, int fr, int fq) const {
;     ...
;             for (int m = 0; m < 4; ++m) { GAS pg8::bf16_t* rowp = O + (size_t)(row0 + ai * 128 + m * 16) * PW + col0;
; #pragma unroll
;                 for (int bj = 0; bj < 2; ++bj) { pg8::f32x4 v0 = acc[ai][bj][m][0] * rsr[ai][m], v1 = acc[ai][bj][m][1] * rsr[ai][m];
;                     if (act == 1) {
; #pragma unroll
;                         for (int e = 0; e < 4; ++e) { v0[e] = silu_f(v0[e]); v1[e] = silu_f(v1[e]); } }
;                     else if (act == 2) {
; #pragma unroll
;                         for (int e = 0; e < 4; ++e) { const float s0 = __builtin_amdgcn_rcpf(1.f + __builtin_amdgcn_exp2f(v0[e] * -1.4426950408889634f)), s1 = __builtin_amdgcn_rcpf(1.f + __builtin_amdgcn_exp2f(v1[e] * -1.4426950408889634f));
;                             v0[e] = __builtin_amdgcn_logf(lbv[bj][0][e] + (1.f - lbv[bj][0][e]) * s0); v1[e] = __builtin_amdgcn_logf(lbv[bj][1][e] + (1.f - lbv[bj][1][e]) * s1);     } }
;                     pg8::u32x4 w; w.x = pg8::cvt_pk_bf16(v0[0], v0[1]); w.y = pg8::cvt_pk_bf16(v0[2], v0[3]); w.z = pg8::cvt_pk_bf16(v1[0], v1[1]); w.w = pg8::cvt_pk_bf16(v1[2], v1[3]);
;                     *(GAS pg8::u32x4*)(rowp + bj * 128) = w; } }
.LBB0_139:
	v_or_b32_e32 v172, 48, v166
	v_ashrrev_i32_e32 v173, 31, v172
	v_lshlrev_b64 v[172:173], 14, v[172:173]
	v_lshl_add_u64 v[172:173], s[12:13], 0, v[172:173]
	v_lshl_add_u64 v[172:173], v[170:171], 1, v[172:173]
	v_cvt_pk_bf16_f32 v174, v210, v212
	v_cvt_pk_bf16_f32 v175, v214, v217
	v_cvt_pk_bf16_f32 v176, v211, v213
	v_cvt_pk_bf16_f32 v177, v215, v216
	v_mov_b32_e32 v180, v165
	v_mov_b32_e32 v181, v165
	v_mov_b32_e32 v178, v165
	v_mov_b32_e32 v179, v165
	global_store_dwordx4 v[172:173], v[174:177], off sc1
	s_cmp_gt_i32 s23, 1
	s_mov_b64 s[0:1], -1
	v_pk_mul_f32 v[174:175], v[70:71], v[178:179]
	v_pk_mul_f32 v[176:177], v[68:69], v[180:181]
	v_pk_mul_f32 v[178:179], v[66:67], v[178:179]
	v_pk_mul_f32 v[180:181], v[64:65], v[180:181]
	s_cbranch_scc0 .LBB0_141
	v_mul_f32_e32 v216, 0xbfb8aa3b, v175
	v_mul_f32_e32 v210, 0xbfb8aa3b, v176
	v_mul_f32_e32 v211, 0xbfb8aa3b, v180
	v_mul_f32_e32 v212, 0xbfb8aa3b, v177
	v_mul_f32_e32 v213, 0xbfb8aa3b, v181
	v_mul_f32_e32 v214, 0xbfb8aa3b, v174
	v_mul_f32_e32 v215, 0xbfb8aa3b, v178
	v_exp_f32_e32 v216, v216
	v_mul_f32_e32 v217, 0xbfb8aa3b, v179
	v_exp_f32_e32 v210, v210
	v_exp_f32_e32 v211, v211
	v_exp_f32_e32 v212, v212
	v_exp_f32_e32 v213, v213
	v_exp_f32_e32 v214, v214
	v_exp_f32_e32 v215, v215
	v_exp_f32_e32 v217, v217
	v_add_f32_e32 v216, 1.0, v216
	v_add_f32_e32 v210, 1.0, v210
	v_add_f32_e32 v211, 1.0, v211
	v_add_f32_e32 v212, 1.0, v212
	v_add_f32_e32 v213, 1.0, v213
	v_add_f32_e32 v214, 1.0, v214
	v_add_f32_e32 v215, 1.0, v215
	v_rcp_f32_e32 v216, v216
	v_add_f32_e32 v217, 1.0, v217
	v_rcp_f32_e32 v210, v210
	v_rcp_f32_e32 v211, v211
	v_rcp_f32_e32 v212, v212
	v_rcp_f32_e32 v213, v213
	v_rcp_f32_e32 v214, v214
	v_rcp_f32_e32 v215, v215
	v_rcp_f32_e32 v218, v217
	v_fma_f32 v216, v216, v195, v137
	v_fma_f32 v210, v210, v203, v134
	v_fma_f32 v211, v211, v202, v130
	v_fma_f32 v212, v212, v199, v135
	v_fma_f32 v213, v213, v198, v131
	v_fma_f32 v214, v214, v197, v136
	v_fma_f32 v215, v215, v196, v132
	v_log_f32_e32 v217, v216
	v_fma_f32 v216, v218, v112, v133
	v_log_f32_e32 v210, v210
	v_log_f32_e32 v211, v211
	v_log_f32_e32 v212, v212
	v_log_f32_e32 v213, v213
	v_log_f32_e32 v214, v214
	v_log_f32_e32 v215, v215
	v_log_f32_e32 v216, v216
	s_mov_b64 s[0:1], 0

; __device__ __forceinline__ unsigned cvt_pk_bf16(float lo, float hi) { unsigned r; asm volatile("v_cvt_pk_bf16_f32 %0, %1, %2" : "=v"(r) : "v"(lo), "v"(hi)); return r; }
; #define GAS __attribute__((address_space(1)))
; __device__ __forceinline__ float silu_f(float x) { return x * __builtin_amdgcn_rcpf(1.f + __builtin_amdgcn_exp2f(x * -1.4426950408889634f)); }
;     __device__ __forceinline__ void operator()(const pg8::f32x4 (&acc)[2][2][4][2], const pg8::Unit& u, int wr, int wc, int fr, int fq) const {
;     ...
;             for (int m = 0; m < 4; ++m) { GAS pg8::bf16_t* rowp = O + (size_t)(row0 + ai * 128 + m * 16) * PW + col0;
; #pragma unroll
;                 for (int bj = 0; bj < 2; ++bj) { pg8::f32x4 v0 = acc[ai][bj][m][0] * rsr[ai][m], v1 = acc[ai][bj][m][1] * rsr[ai][m];
;                     if (act == 1) {
; #pragma unroll
;                         for (int e = 0; e < 4; ++e) { v0[e] = silu_f(v0[e]); v1[e] = silu_f(v1[e]); } }
;                     else if (act == 2) {
; #pragma unroll
;                         for (int e = 0; e < 4; ++e) { const float s0 = __builtin_amdgcn_rcpf(1.f + __builtin_amdgcn_exp2f(v0[e] * -1.4426950408889634f)), s1 = __builtin_amdgcn_rcpf(1.f + __builtin_amdgcn_exp2f(v1[e] * -1.4426950408889634f));
;                             v0[e] = __builtin_amdgcn_logf(lbv[bj][0][e] + (1.f - lbv[bj][0][e]) * s0); v1[e] = __builtin_amdgcn_logf(lbv[bj][1][e] + (1.f - lbv[bj][1][e]) * s1);     } }
;                     pg8::u32x4 w; w.x = pg8::cvt_pk_bf16(v0[0], v0[1]); w.y = pg8::cvt_pk_bf16(v0[2], v0[3]); w.z = pg8::cvt_pk_bf16(v1[0], v1[1]); w.w = pg8::cvt_pk_bf16(v1[2], v1[3]);
;                     *(GAS pg8::u32x4*)(rowp + bj * 128) = w; } }
.LBB0_145:
	v_cvt_pk_bf16_f32 v174, v210, v212
	v_cvt_pk_bf16_f32 v175, v214, v217
	v_cvt_pk_bf16_f32 v176, v211, v213
	v_cvt_pk_bf16_f32 v177, v215, v216
	global_store_dwordx4 v[172:173], v[174:177], off offset:256 sc1
	v_pk_mul_f32 v[172:173], v[62:63], v[162:163] op_sel_hi:[1,0]
	v_pk_mul_f32 v[178:179], v[56:57], v[162:163] op_sel_hi:[1,0]
	v_pk_mul_f32 v[174:175], v[60:61], v[162:163] op_sel_hi:[1,0]
	v_pk_mul_f32 v[176:177], v[58:59], v[162:163] op_sel_hi:[1,0]
	s_cmp_gt_i32 s23, 1
	s_mov_b64 s[0:1], -1
	s_cbranch_scc0 .LBB0_147
	v_mul_f32_e32 v180, 0xbfb8aa3b, v174
	v_exp_f32_e32 v180, v180
	v_mul_f32_e32 v181, 0xbfb8aa3b, v178
	v_exp_f32_e32 v181, v181
	v_mul_f32_e32 v210, 0xbfb8aa3b, v175
	v_add_f32_e32 v180, 1.0, v180
	v_rcp_f32_e32 v180, v180
	v_add_f32_e32 v181, 1.0, v181
	v_rcp_f32_e32 v181, v181
	v_exp_f32_e32 v211, v210
	v_fma_f32 v180, v180, v209, v142
	v_log_f32_e32 v210, v180
	v_fma_f32 v180, v181, v208, v138
	v_mul_f32_e32 v181, 0xbfb8aa3b, v179
	v_add_f32_e32 v211, 1.0, v211
	v_exp_f32_e32 v181, v181
	v_rcp_f32_e32 v212, v211
	v_log_f32_e32 v211, v180
	v_mul_f32_e32 v213, 0xbfb8aa3b, v176
	v_add_f32_e32 v180, 1.0, v181
	v_fma_f32 v181, v212, v207, v143
	v_log_f32_e32 v212, v181
	v_mul_f32_e32 v181, 0xbfb8aa3b, v172
	v_exp_f32_e32 v181, v181
	v_rcp_f32_e32 v180, v180
	v_exp_f32_e32 v214, v213
	v_mul_f32_e32 v215, 0xbfb8aa3b, v177
	v_add_f32_e32 v181, 1.0, v181
	v_rcp_f32_e32 v181, v181
	v_fma_f32 v180, v180, v206, v139
	v_log_f32_e32 v213, v180
	v_add_f32_e32 v180, 1.0, v214
	v_fma_f32 v181, v181, v205, v144
	v_log_f32_e32 v214, v181
	v_mul_f32_e32 v181, 0xbfb8aa3b, v173
	v_exp_f32_e32 v181, v181
	v_exp_f32_e32 v215, v215
	v_rcp_f32_e32 v180, v180
	s_mov_b64 s[0:1], 0
	v_add_f32_e32 v181, 1.0, v181
	v_rcp_f32_e32 v181, v181
	v_add_f32_e32 v215, 1.0, v215
	v_rcp_f32_e32 v216, v215
	v_fma_f32 v180, v180, v204, v140
	v_log_f32_e32 v215, v180
	v_fma_f32 v180, v181, v201, v145
	v_log_f32_e32 v217, v180
	v_fma_f32 v180, v216, v200, v141
	v_log_f32_e32 v216, v180

; __device__ __forceinline__ unsigned cvt_pk_bf16(float lo, float hi) { unsigned r; asm volatile("v_cvt_pk_bf16_f32 %0, %1, %2" : "=v"(r) : "v"(lo), "v"(hi)); return r; }
; #define GAS __attribute__((address_space(1)))
; __device__ __forceinline__ float silu_f(float x) { return x * __builtin_amdgcn_rcpf(1.f + __builtin_amdgcn_exp2f(x * -1.4426950408889634f)); }
;     __device__ __forceinline__ void operator()(const pg8::f32x4 (&acc)[2][2][4][2], const pg8::Unit& u, int wr, int wc, int fr, int fq) const {
;     ...
;             for (int m = 0; m < 4; ++m) { GAS pg8::bf16_t* rowp = O + (size_t)(row0 + ai * 128 + m * 16) * PW + col0;
; #pragma unroll
;                 for (int bj = 0; bj < 2; ++bj) { pg8::f32x4 v0 = acc[ai][bj][m][0] * rsr[ai][m], v1 = acc[ai][bj][m][1] * rsr[ai][m];
;                     if (act == 1) {
; #pragma unroll
;                         for (int e = 0; e < 4; ++e) { v0[e] = silu_f(v0[e]); v1[e] = silu_f(v1[e]); } }
;                     else if (act == 2) {
; #pragma unroll
;                         for (int e = 0; e < 4; ++e) { const float s0 = __builtin_amdgcn_rcpf(1.f + __builtin_amdgcn_exp2f(v0[e] * -1.4426950408889634f)), s1 = __builtin_amdgcn_rcpf(1.f + __builtin_amdgcn_exp2f(v1[e] * -1.4426950408889634f));
;                             v0[e] = __builtin_amdgcn_logf(lbv[bj][0][e] + (1.f - lbv[bj][0][e]) * s0); v1[e] = __builtin_amdgcn_logf(lbv[bj][1][e] + (1.f - lbv[bj][1][e]) * s1);     } }
;                     pg8::u32x4 w; w.x = pg8::cvt_pk_bf16(v0[0], v0[1]); w.y = pg8::cvt_pk_bf16(v0[2], v0[3]); w.z = pg8::cvt_pk_bf16(v1[0], v1[1]); w.w = pg8::cvt_pk_bf16(v1[2], v1[3]);
;                     *(GAS pg8::u32x4*)(rowp + bj * 128) = w; } }
.LBB0_151:
	v_lshlrev_b64 v[172:173], 14, v[166:167]
	v_lshl_add_u64 v[172:173], s[12:13], 0, v[172:173]
	v_lshl_add_u64 v[178:179], v[170:171], 1, v[172:173]
	s_mov_b64 s[0:1], 0x200000
	v_lshl_add_u64 v[172:173], v[178:179], 0, s[0:1]
	v_add_co_u32_e32 v178, vcc, 0x200000, v178
	v_cvt_pk_bf16_f32 v174, v210, v212
	v_cvt_pk_bf16_f32 v175, v214, v217
	v_cvt_pk_bf16_f32 v176, v211, v213
	v_cvt_pk_bf16_f32 v177, v215, v216
	s_nop 1
	v_addc_co_u32_e32 v179, vcc, 0, v179, vcc
	global_store_dwordx4 v[178:179], v[174:177], off sc1
	v_mov_b32_e32 v180, v162
	v_mov_b32_e32 v181, v162
	v_mov_b32_e32 v178, v162
	v_mov_b32_e32 v179, v162
	v_pk_mul_f32 v[174:175], v[54:55], v[178:179]
	v_pk_mul_f32 v[176:177], v[52:53], v[180:181]
	v_pk_mul_f32 v[178:179], v[46:47], v[178:179]
	v_pk_mul_f32 v[180:181], v[44:45], v[180:181]
	s_cmp_gt_i32 s23, 1
	s_mov_b64 s[0:1], -1
	s_cbranch_scc0 .LBB0_153
	v_mul_f32_e32 v216, 0xbfb8aa3b, v175
	v_mul_f32_e32 v210, 0xbfb8aa3b, v176
	v_mul_f32_e32 v211, 0xbfb8aa3b, v180
	v_mul_f32_e32 v212, 0xbfb8aa3b, v177
	v_mul_f32_e32 v213, 0xbfb8aa3b, v181
	v_mul_f32_e32 v214, 0xbfb8aa3b, v174
	v_mul_f32_e32 v215, 0xbfb8aa3b, v178
	v_exp_f32_e32 v216, v216
	v_mul_f32_e32 v217, 0xbfb8aa3b, v179
	v_exp_f32_e32 v210, v210
	v_exp_f32_e32 v211, v211
	v_exp_f32_e32 v212, v212
	v_exp_f32_e32 v213, v213
	v_exp_f32_e32 v214, v214
	v_exp_f32_e32 v215, v215
	v_exp_f32_e32 v217, v217
	v_add_f32_e32 v216, 1.0, v216
	v_add_f32_e32 v210, 1.0, v210
	v_add_f32_e32 v211, 1.0, v211
	v_add_f32_e32 v212, 1.0, v212
	v_add_f32_e32 v213, 1.0, v213
	v_add_f32_e32 v214, 1.0, v214
	v_add_f32_e32 v215, 1.0, v215
	v_rcp_f32_e32 v216, v216
	v_add_f32_e32 v217, 1.0, v217
	v_rcp_f32_e32 v210, v210
	v_rcp_f32_e32 v211, v211
	v_rcp_f32_e32 v212, v212
	v_rcp_f32_e32 v213, v213
	v_rcp_f32_e32 v214, v214
	v_rcp_f32_e32 v215, v215
	v_rcp_f32_e32 v218, v217
	v_fma_f32 v216, v216, v195, v137
	v_fma_f32 v210, v210, v203, v134
	v_fma_f32 v211, v211, v202, v130
	v_fma_f32 v212, v212, v199, v135
	v_fma_f32 v213, v213, v198, v131
	v_fma_f32 v214, v214, v197, v136
	v_fma_f32 v215, v215, v196, v132
	v_log_f32_e32 v217, v216
	v_fma_f32 v216, v218, v112, v133
	v_log_f32_e32 v210, v210
	v_log_f32_e32 v211, v211
	v_log_f32_e32 v212, v212
	v_log_f32_e32 v213, v213
	v_log_f32_e32 v214, v214
	v_log_f32_e32 v215, v215
	v_log_f32_e32 v216, v216
	s_mov_b64 s[0:1], 0

; __device__ __forceinline__ unsigned cvt_pk_bf16(float lo, float hi) { unsigned r; asm volatile("v_cvt_pk_bf16_f32 %0, %1, %2" : "=v"(r) : "v"(lo), "v"(hi)); return r; }
; #define GAS __attribute__((address_space(1)))
; __device__ __forceinline__ float silu_f(float x) { return x * __builtin_amdgcn_rcpf(1.f + __builtin_amdgcn_exp2f(x * -1.4426950408889634f)); }
;     __device__ __forceinline__ void operator()(const pg8::f32x4 (&acc)[2][2][4][2], const pg8::Unit& u, int wr, int wc, int fr, int fq) const {
;     ...
;             for (int m = 0; m < 4; ++m) { GAS pg8::bf16_t* rowp = O + (size_t)(row0 + ai * 128 + m * 16) * PW + col0;
; #pragma unroll
;                 for (int bj = 0; bj < 2; ++bj) { pg8::f32x4 v0 = acc[ai][bj][m][0] * rsr[ai][m], v1 = acc[ai][bj][m][1] * rsr[ai][m];
;                     if (act == 1) {
; #pragma unroll
;                         for (int e = 0; e < 4; ++e) { v0[e] = silu_f(v0[e]); v1[e] = silu_f(v1[e]); } }
;                     else if (act == 2) {
; #pragma unroll
;                         for (int e = 0; e < 4; ++e) { const float s0 = __builtin_amdgcn_rcpf(1.f + __builtin_amdgcn_exp2f(v0[e] * -1.4426950408889634f)), s1 = __builtin_amdgcn_rcpf(1.f + __builtin_amdgcn_exp2f(v1[e] * -1.4426950408889634f));
;                             v0[e] = __builtin_amdgcn_logf(lbv[bj][0][e] + (1.f - lbv[bj][0][e]) * s0); v1[e] = __builtin_amdgcn_logf(lbv[bj][1][e] + (1.f - lbv[bj][1][e]) * s1);     } }
;                     pg8::u32x4 w; w.x = pg8::cvt_pk_bf16(v0[0], v0[1]); w.y = pg8::cvt_pk_bf16(v0[2], v0[3]); w.z = pg8::cvt_pk_bf16(v1[0], v1[1]); w.w = pg8::cvt_pk_bf16(v1[2], v1[3]);
;                     *(GAS pg8::u32x4*)(rowp + bj * 128) = w; } }
.LBB0_157:
	v_cvt_pk_bf16_f32 v174, v210, v212
	v_cvt_pk_bf16_f32 v175, v214, v217
	v_cvt_pk_bf16_f32 v176, v211, v213
	v_cvt_pk_bf16_f32 v177, v215, v216
	v_mov_b32_e32 v178, v163
	global_store_dwordx4 v[172:173], v[174:177], off offset:256 sc1
	v_pk_mul_f32 v[172:173], v[50:51], v[178:179] op_sel_hi:[1,0]
	s_cmp_gt_i32 s23, 1
	v_pk_mul_f32 v[174:175], v[48:49], v[178:179] op_sel_hi:[1,0]
	v_pk_mul_f32 v[176:177], v[42:43], v[178:179] op_sel_hi:[1,0]
	v_pk_mul_f32 v[178:179], v[40:41], v[178:179] op_sel_hi:[1,0]
	s_mov_b64 s[0:1], -1
	s_cbranch_scc0 .LBB0_159
	v_mul_f32_e32 v180, 0xbfb8aa3b, v174
	v_exp_f32_e32 v180, v180
	v_mul_f32_e32 v181, 0xbfb8aa3b, v178
	v_exp_f32_e32 v181, v181
	v_mul_f32_e32 v210, 0xbfb8aa3b, v175
	v_add_f32_e32 v180, 1.0, v180
	v_rcp_f32_e32 v180, v180
	v_add_f32_e32 v181, 1.0, v181
	v_rcp_f32_e32 v181, v181
	v_exp_f32_e32 v211, v210
	v_fma_f32 v180, v180, v209, v142
	v_log_f32_e32 v210, v180
	v_fma_f32 v180, v181, v208, v138
	v_mul_f32_e32 v181, 0xbfb8aa3b, v179
	v_add_f32_e32 v211, 1.0, v211
	v_exp_f32_e32 v181, v181
	v_rcp_f32_e32 v212, v211
	v_log_f32_e32 v211, v180
	v_mul_f32_e32 v213, 0xbfb8aa3b, v176
	v_add_f32_e32 v180, 1.0, v181
	v_fma_f32 v181, v212, v207, v143
	v_log_f32_e32 v212, v181
	v_mul_f32_e32 v181, 0xbfb8aa3b, v172
	v_exp_f32_e32 v181, v181
	v_rcp_f32_e32 v180, v180
	v_exp_f32_e32 v214, v213
	v_mul_f32_e32 v215, 0xbfb8aa3b, v177
	v_add_f32_e32 v181, 1.0, v181
	v_rcp_f32_e32 v181, v181
	v_fma_f32 v180, v180, v206, v139
	v_log_f32_e32 v213, v180
	v_add_f32_e32 v180, 1.0, v214
	v_fma_f32 v181, v181, v205, v144
	v_log_f32_e32 v214, v181
	v_mul_f32_e32 v181, 0xbfb8aa3b, v173
	v_exp_f32_e32 v181, v181
	v_exp_f32_e32 v215, v215
	v_rcp_f32_e32 v180, v180
	s_mov_b64 s[0:1], 0
	v_add_f32_e32 v181, 1.0, v181
	v_rcp_f32_e32 v181, v181
	v_add_f32_e32 v215, 1.0, v215
	v_rcp_f32_e32 v216, v215
	v_fma_f32 v180, v180, v204, v140
	v_log_f32_e32 v215, v180
	v_fma_f32 v180, v181, v201, v145
	v_log_f32_e32 v217, v180
	v_fma_f32 v180, v216, v200, v141
	v_log_f32_e32 v216, v180

; __device__ __forceinline__ unsigned cvt_pk_bf16(float lo, float hi) { unsigned r; asm volatile("v_cvt_pk_bf16_f32 %0, %1, %2" : "=v"(r) : "v"(lo), "v"(hi)); return r; }
; #define GAS __attribute__((address_space(1)))
; __device__ __forceinline__ float silu_f(float x) { return x * __builtin_amdgcn_rcpf(1.f + __builtin_amdgcn_exp2f(x * -1.4426950408889634f)); }
;     __device__ __forceinline__ void operator()(const pg8::f32x4 (&acc)[2][2][4][2], const pg8::Unit& u, int wr, int wc, int fr, int fq) const {
;     ...
;             for (int m = 0; m < 4; ++m) { GAS pg8::bf16_t* rowp = O + (size_t)(row0 + ai * 128 + m * 16) * PW + col0;
; #pragma unroll
;                 for (int bj = 0; bj < 2; ++bj) { pg8::f32x4 v0 = acc[ai][bj][m][0] * rsr[ai][m], v1 = acc[ai][bj][m][1] * rsr[ai][m];
;                     if (act == 1) {
; #pragma unroll
;                         for (int e = 0; e < 4; ++e) { v0[e] = silu_f(v0[e]); v1[e] = silu_f(v1[e]); } }
;                     else if (act == 2) {
; #pragma unroll
;                         for (int e = 0; e < 4; ++e) { const float s0 = __builtin_amdgcn_rcpf(1.f + __builtin_amdgcn_exp2f(v0[e] * -1.4426950408889634f)), s1 = __builtin_amdgcn_rcpf(1.f + __builtin_amdgcn_exp2f(v1[e] * -1.4426950408889634f));
;                             v0[e] = __builtin_amdgcn_logf(lbv[bj][0][e] + (1.f - lbv[bj][0][e]) * s0); v1[e] = __builtin_amdgcn_logf(lbv[bj][1][e] + (1.f - lbv[bj][1][e]) * s1);     } }
;                     pg8::u32x4 w; w.x = pg8::cvt_pk_bf16(v0[0], v0[1]); w.y = pg8::cvt_pk_bf16(v0[2], v0[3]); w.z = pg8::cvt_pk_bf16(v1[0], v1[1]); w.w = pg8::cvt_pk_bf16(v1[2], v1[3]);
;                     *(GAS pg8::u32x4*)(rowp + bj * 128) = w; } }
.LBB0_163:
	v_lshlrev_b64 v[172:173], 14, v[166:167]
	v_lshl_add_u64 v[172:173], s[12:13], 0, v[172:173]
	v_lshl_add_u64 v[178:179], v[170:171], 1, v[172:173]
	s_mov_b64 s[0:1], 0x240000
	v_lshl_add_u64 v[172:173], v[178:179], 0, s[0:1]
	v_add_co_u32_e32 v178, vcc, 0x240000, v178
	v_cvt_pk_bf16_f32 v174, v210, v212
	v_cvt_pk_bf16_f32 v175, v214, v217
	v_cvt_pk_bf16_f32 v176, v211, v213
	v_cvt_pk_bf16_f32 v177, v215, v216
	s_nop 1
	v_addc_co_u32_e32 v179, vcc, 0, v179, vcc
	global_store_dwordx4 v[178:179], v[174:177], off sc1
	v_mov_b32_e32 v180, v163
	v_mov_b32_e32 v181, v163
	v_mov_b32_e32 v178, v163
	v_mov_b32_e32 v179, v163
	v_pk_mul_f32 v[174:175], v[38:39], v[178:179]
	v_pk_mul_f32 v[176:177], v[36:37], v[180:181]
	v_pk_mul_f32 v[178:179], v[30:31], v[178:179]
	v_pk_mul_f32 v[180:181], v[28:29], v[180:181]
	s_cmp_gt_i32 s23, 1
	s_mov_b64 s[0:1], -1
	s_cbranch_scc0 .LBB0_165
	v_mul_f32_e32 v216, 0xbfb8aa3b, v175
	v_mul_f32_e32 v210, 0xbfb8aa3b, v176
	v_mul_f32_e32 v211, 0xbfb8aa3b, v180
	v_mul_f32_e32 v212, 0xbfb8aa3b, v177
	v_mul_f32_e32 v213, 0xbfb8aa3b, v181
	v_mul_f32_e32 v214, 0xbfb8aa3b, v174
	v_mul_f32_e32 v215, 0xbfb8aa3b, v178
	v_exp_f32_e32 v216, v216
	v_mul_f32_e32 v217, 0xbfb8aa3b, v179
	v_exp_f32_e32 v210, v210
	v_exp_f32_e32 v211, v211
	v_exp_f32_e32 v212, v212
	v_exp_f32_e32 v213, v213
	v_exp_f32_e32 v214, v214
	v_exp_f32_e32 v215, v215
	v_exp_f32_e32 v217, v217
	v_add_f32_e32 v216, 1.0, v216
	v_add_f32_e32 v210, 1.0, v210
	v_add_f32_e32 v211, 1.0, v211
	v_add_f32_e32 v212, 1.0, v212
	v_add_f32_e32 v213, 1.0, v213
	v_add_f32_e32 v214, 1.0, v214
	v_add_f32_e32 v215, 1.0, v215
	v_rcp_f32_e32 v216, v216
	v_add_f32_e32 v217, 1.0, v217
	v_rcp_f32_e32 v210, v210
	v_rcp_f32_e32 v211, v211
	v_rcp_f32_e32 v212, v212
	v_rcp_f32_e32 v213, v213
	v_rcp_f32_e32 v214, v214
	v_rcp_f32_e32 v215, v215
	v_rcp_f32_e32 v218, v217
	v_fma_f32 v216, v216, v195, v137
	v_fma_f32 v210, v210, v203, v134
	v_fma_f32 v211, v211, v202, v130
	v_fma_f32 v212, v212, v199, v135
	v_fma_f32 v213, v213, v198, v131
	v_fma_f32 v214, v214, v197, v136
	v_fma_f32 v215, v215, v196, v132
	v_log_f32_e32 v217, v216
	v_fma_f32 v216, v218, v112, v133
	v_log_f32_e32 v210, v210
	v_log_f32_e32 v211, v211
	v_log_f32_e32 v212, v212
	v_log_f32_e32 v213, v213
	v_log_f32_e32 v214, v214
	v_log_f32_e32 v215, v215
	v_log_f32_e32 v216, v216
	s_mov_b64 s[0:1], 0

; __device__ __forceinline__ unsigned cvt_pk_bf16(float lo, float hi) { unsigned r; asm volatile("v_cvt_pk_bf16_f32 %0, %1, %2" : "=v"(r) : "v"(lo), "v"(hi)); return r; }
; #define GAS __attribute__((address_space(1)))
; __device__ __forceinline__ float silu_f(float x) { return x * __builtin_amdgcn_rcpf(1.f + __builtin_amdgcn_exp2f(x * -1.4426950408889634f)); }
;     __device__ __forceinline__ void operator()(const pg8::f32x4 (&acc)[2][2][4][2], const pg8::Unit& u, int wr, int wc, int fr, int fq) const {
;     ...
;             for (int m = 0; m < 4; ++m) { GAS pg8::bf16_t* rowp = O + (size_t)(row0 + ai * 128 + m * 16) * PW + col0;
; #pragma unroll
;                 for (int bj = 0; bj < 2; ++bj) { pg8::f32x4 v0 = acc[ai][bj][m][0] * rsr[ai][m], v1 = acc[ai][bj][m][1] * rsr[ai][m];
;                     if (act == 1) {
; #pragma unroll
;                         for (int e = 0; e < 4; ++e) { v0[e] = silu_f(v0[e]); v1[e] = silu_f(v1[e]); } }
;                     else if (act == 2) {
; #pragma unroll
;                         for (int e = 0; e < 4; ++e) { const float s0 = __builtin_amdgcn_rcpf(1.f + __builtin_amdgcn_exp2f(v0[e] * -1.4426950408889634f)), s1 = __builtin_amdgcn_rcpf(1.f + __builtin_amdgcn_exp2f(v1[e] * -1.4426950408889634f));
;                             v0[e] = __builtin_amdgcn_logf(lbv[bj][0][e] + (1.f - lbv[bj][0][e]) * s0); v1[e] = __builtin_amdgcn_logf(lbv[bj][1][e] + (1.f - lbv[bj][1][e]) * s1);     } }
;                     pg8::u32x4 w; w.x = pg8::cvt_pk_bf16(v0[0], v0[1]); w.y = pg8::cvt_pk_bf16(v0[2], v0[3]); w.z = pg8::cvt_pk_bf16(v1[0], v1[1]); w.w = pg8::cvt_pk_bf16(v1[2], v1[3]);
;                     *(GAS pg8::u32x4*)(rowp + bj * 128) = w; } }
.LBB0_169:
	v_cvt_pk_bf16_f32 v174, v210, v212
	v_cvt_pk_bf16_f32 v175, v214, v217
	v_cvt_pk_bf16_f32 v176, v211, v213
	v_cvt_pk_bf16_f32 v177, v215, v216
	global_store_dwordx4 v[172:173], v[174:177], off offset:256 sc1
	v_pk_mul_f32 v[172:173], v[34:35], v[160:161] op_sel_hi:[1,0]
	v_pk_mul_f32 v[178:179], v[24:25], v[160:161] op_sel_hi:[1,0]
	v_pk_mul_f32 v[174:175], v[32:33], v[160:161] op_sel_hi:[1,0]
	v_pk_mul_f32 v[176:177], v[26:27], v[160:161] op_sel_hi:[1,0]
	s_cmp_gt_i32 s23, 1
	s_mov_b64 s[0:1], -1
	s_cbranch_scc0 .LBB0_171
	v_mul_f32_e32 v180, 0xbfb8aa3b, v174
	v_exp_f32_e32 v180, v180
	v_mul_f32_e32 v181, 0xbfb8aa3b, v178
	v_exp_f32_e32 v181, v181
	v_mul_f32_e32 v210, 0xbfb8aa3b, v175
	v_add_f32_e32 v180, 1.0, v180
	v_rcp_f32_e32 v180, v180
	v_add_f32_e32 v181, 1.0, v181
	v_rcp_f32_e32 v181, v181
	v_exp_f32_e32 v211, v210
	v_fma_f32 v180, v180, v209, v142
	v_log_f32_e32 v210, v180
	v_fma_f32 v180, v181, v208, v138
	v_mul_f32_e32 v181, 0xbfb8aa3b, v179
	v_add_f32_e32 v211, 1.0, v211
	v_exp_f32_e32 v181, v181
	v_rcp_f32_e32 v212, v211
	v_log_f32_e32 v211, v180
	v_mul_f32_e32 v213, 0xbfb8aa3b, v176
	v_add_f32_e32 v180, 1.0, v181
	v_fma_f32 v181, v212, v207, v143
	v_log_f32_e32 v212, v181
	v_mul_f32_e32 v181, 0xbfb8aa3b, v172
	v_exp_f32_e32 v181, v181
	v_rcp_f32_e32 v180, v180
	v_exp_f32_e32 v214, v213
	v_mul_f32_e32 v215, 0xbfb8aa3b, v177
	v_add_f32_e32 v181, 1.0, v181
	v_rcp_f32_e32 v181, v181
	v_fma_f32 v180, v180, v206, v139
	v_log_f32_e32 v213, v180
	v_add_f32_e32 v180, 1.0, v214
	v_fma_f32 v181, v181, v205, v144
	v_log_f32_e32 v214, v181
	v_mul_f32_e32 v181, 0xbfb8aa3b, v173
	v_exp_f32_e32 v181, v181
	v_exp_f32_e32 v215, v215
	v_rcp_f32_e32 v180, v180
	s_mov_b64 s[0:1], 0
	v_add_f32_e32 v181, 1.0, v181
	v_rcp_f32_e32 v181, v181
	v_add_f32_e32 v215, 1.0, v215
	v_rcp_f32_e32 v216, v215
	v_fma_f32 v180, v180, v204, v140
	v_log_f32_e32 v215, v180
	v_fma_f32 v180, v181, v201, v145
	v_log_f32_e32 v217, v180
	v_fma_f32 v180, v216, v200, v141
	v_log_f32_e32 v216, v180

; __device__ __forceinline__ unsigned cvt_pk_bf16(float lo, float hi) { unsigned r; asm volatile("v_cvt_pk_bf16_f32 %0, %1, %2" : "=v"(r) : "v"(lo), "v"(hi)); return r; }
; #define GAS __attribute__((address_space(1)))
; __device__ __forceinline__ float silu_f(float x) { return x * __builtin_amdgcn_rcpf(1.f + __builtin_amdgcn_exp2f(x * -1.4426950408889634f)); }
;     __device__ __forceinline__ void operator()(const pg8::f32x4 (&acc)[2][2][4][2], const pg8::Unit& u, int wr, int wc, int fr, int fq) const {
;     ...
;             for (int m = 0; m < 4; ++m) { GAS pg8::bf16_t* rowp = O + (size_t)(row0 + ai * 128 + m * 16) * PW + col0;
; #pragma unroll
;                 for (int bj = 0; bj < 2; ++bj) { pg8::f32x4 v0 = acc[ai][bj][m][0] * rsr[ai][m], v1 = acc[ai][bj][m][1] * rsr[ai][m];
;                     if (act == 1) {
; #pragma unroll
;                         for (int e = 0; e < 4; ++e) { v0[e] = silu_f(v0[e]); v1[e] = silu_f(v1[e]); } }
;                     else if (act == 2) {
; #pragma unroll
;                         for (int e = 0; e < 4; ++e) { const float s0 = __builtin_amdgcn_rcpf(1.f + __builtin_amdgcn_exp2f(v0[e] * -1.4426950408889634f)), s1 = __builtin_amdgcn_rcpf(1.f + __builtin_amdgcn_exp2f(v1[e] * -1.4426950408889634f));
;                             v0[e] = __builtin_amdgcn_logf(lbv[bj][0][e] + (1.f - lbv[bj][0][e]) * s0); v1[e] = __builtin_amdgcn_logf(lbv[bj][1][e] + (1.f - lbv[bj][1][e]) * s1);     } }
;                     pg8::u32x4 w; w.x = pg8::cvt_pk_bf16(v0[0], v0[1]); w.y = pg8::cvt_pk_bf16(v0[2], v0[3]); w.z = pg8::cvt_pk_bf16(v1[0], v1[1]); w.w = pg8::cvt_pk_bf16(v1[2], v1[3]);
;                     *(GAS pg8::u32x4*)(rowp + bj * 128) = w; } }
.LBB0_175:
	v_lshlrev_b64 v[172:173], 14, v[166:167]
	v_lshl_add_u64 v[172:173], s[12:13], 0, v[172:173]
	v_lshl_add_u64 v[178:179], v[170:171], 1, v[172:173]
	s_mov_b64 s[0:1], 0x280000
	v_lshl_add_u64 v[172:173], v[178:179], 0, s[0:1]
	v_add_co_u32_e32 v178, vcc, 0x280000, v178
	v_cvt_pk_bf16_f32 v174, v210, v212
	v_cvt_pk_bf16_f32 v175, v214, v217
	v_cvt_pk_bf16_f32 v176, v211, v213
	v_cvt_pk_bf16_f32 v177, v215, v216
	s_nop 1
	v_addc_co_u32_e32 v179, vcc, 0, v179, vcc
	global_store_dwordx4 v[178:179], v[174:177], off sc1
	v_mov_b32_e32 v180, v160
	v_mov_b32_e32 v181, v160
	v_mov_b32_e32 v178, v160
	v_mov_b32_e32 v179, v160
	v_pk_mul_f32 v[174:175], v[22:23], v[178:179]
	v_pk_mul_f32 v[176:177], v[20:21], v[180:181]
	v_pk_mul_f32 v[178:179], v[14:15], v[178:179]
	v_pk_mul_f32 v[180:181], v[12:13], v[180:181]
	s_cmp_gt_i32 s23, 1
	s_mov_b64 s[0:1], -1
	s_cbranch_scc0 .LBB0_177
	v_mul_f32_e32 v216, 0xbfb8aa3b, v175
	v_mul_f32_e32 v210, 0xbfb8aa3b, v176
	v_mul_f32_e32 v211, 0xbfb8aa3b, v180
	v_mul_f32_e32 v212, 0xbfb8aa3b, v177
	v_mul_f32_e32 v213, 0xbfb8aa3b, v181
	v_mul_f32_e32 v214, 0xbfb8aa3b, v174
	v_mul_f32_e32 v215, 0xbfb8aa3b, v178
	v_exp_f32_e32 v216, v216
	v_mul_f32_e32 v217, 0xbfb8aa3b, v179
	v_exp_f32_e32 v210, v210
	v_exp_f32_e32 v211, v211
	v_exp_f32_e32 v212, v212
	v_exp_f32_e32 v213, v213
	v_exp_f32_e32 v214, v214
	v_exp_f32_e32 v215, v215
	v_exp_f32_e32 v217, v217
	v_add_f32_e32 v216, 1.0, v216
	v_add_f32_e32 v210, 1.0, v210
	v_add_f32_e32 v211, 1.0, v211
	v_add_f32_e32 v212, 1.0, v212
	v_add_f32_e32 v213, 1.0, v213
	v_add_f32_e32 v214, 1.0, v214
	v_add_f32_e32 v215, 1.0, v215
	v_rcp_f32_e32 v216, v216
	v_add_f32_e32 v217, 1.0, v217
	v_rcp_f32_e32 v210, v210
	v_rcp_f32_e32 v211, v211
	v_rcp_f32_e32 v212, v212
	v_rcp_f32_e32 v213, v213
	v_rcp_f32_e32 v214, v214
	v_rcp_f32_e32 v215, v215
	v_rcp_f32_e32 v218, v217
	v_fma_f32 v216, v216, v195, v137
	v_fma_f32 v210, v210, v203, v134
	v_fma_f32 v211, v211, v202, v130
	v_fma_f32 v212, v212, v199, v135
	v_fma_f32 v213, v213, v198, v131
	v_fma_f32 v214, v214, v197, v136
	v_fma_f32 v215, v215, v196, v132
	v_log_f32_e32 v217, v216
	v_fma_f32 v216, v218, v112, v133
	v_log_f32_e32 v210, v210
	v_log_f32_e32 v211, v211
	v_log_f32_e32 v212, v212
	v_log_f32_e32 v213, v213
	v_log_f32_e32 v214, v214
	v_log_f32_e32 v215, v215
	v_log_f32_e32 v216, v216
	s_mov_b64 s[0:1], 0

; __device__ __forceinline__ unsigned cvt_pk_bf16(float lo, float hi) { unsigned r; asm volatile("v_cvt_pk_bf16_f32 %0, %1, %2" : "=v"(r) : "v"(lo), "v"(hi)); return r; }
; #define GAS __attribute__((address_space(1)))
; __device__ __forceinline__ float silu_f(float x) { return x * __builtin_amdgcn_rcpf(1.f + __builtin_amdgcn_exp2f(x * -1.4426950408889634f)); }
;     __device__ __forceinline__ void operator()(const pg8::f32x4 (&acc)[2][2][4][2], const pg8::Unit& u, int wr, int wc, int fr, int fq) const {
;     ...
;             for (int m = 0; m < 4; ++m) { GAS pg8::bf16_t* rowp = O + (size_t)(row0 + ai * 128 + m * 16) * PW + col0;
; #pragma unroll
;                 for (int bj = 0; bj < 2; ++bj) { pg8::f32x4 v0 = acc[ai][bj][m][0] * rsr[ai][m], v1 = acc[ai][bj][m][1] * rsr[ai][m];
;                     if (act == 1) {
; #pragma unroll
;                         for (int e = 0; e < 4; ++e) { v0[e] = silu_f(v0[e]); v1[e] = silu_f(v1[e]); } }
;                     else if (act == 2) {
; #pragma unroll
;                         for (int e = 0; e < 4; ++e) { const float s0 = __builtin_amdgcn_rcpf(1.f + __builtin_amdgcn_exp2f(v0[e] * -1.4426950408889634f)), s1 = __builtin_amdgcn_rcpf(1.f + __builtin_amdgcn_exp2f(v1[e] * -1.4426950408889634f));
;                             v0[e] = __builtin_amdgcn_logf(lbv[bj][0][e] + (1.f - lbv[bj][0][e]) * s0); v1[e] = __builtin_amdgcn_logf(lbv[bj][1][e] + (1.f - lbv[bj][1][e]) * s1);     } }
;                     pg8::u32x4 w; w.x = pg8::cvt_pk_bf16(v0[0], v0[1]); w.y = pg8::cvt_pk_bf16(v0[2], v0[3]); w.z = pg8::cvt_pk_bf16(v1[0], v1[1]); w.w = pg8::cvt_pk_bf16(v1[2], v1[3]);
;                     *(GAS pg8::u32x4*)(rowp + bj * 128) = w; } }
.LBB0_181:
	v_cvt_pk_bf16_f32 v174, v210, v212
	v_cvt_pk_bf16_f32 v175, v214, v217
	v_cvt_pk_bf16_f32 v176, v211, v213
	v_cvt_pk_bf16_f32 v177, v215, v216
	v_mov_b32_e32 v178, v161
	global_store_dwordx4 v[172:173], v[174:177], off offset:256 sc1
	v_pk_mul_f32 v[172:173], v[18:19], v[178:179] op_sel_hi:[1,0]
	s_cmp_gt_i32 s23, 1
	v_pk_mul_f32 v[174:175], v[16:17], v[178:179] op_sel_hi:[1,0]
	v_pk_mul_f32 v[176:177], v[10:11], v[178:179] op_sel_hi:[1,0]
	v_pk_mul_f32 v[178:179], v[8:9], v[178:179] op_sel_hi:[1,0]
	s_mov_b64 s[0:1], -1
	s_cbranch_scc0 .LBB0_183
	v_mul_f32_e32 v180, 0xbfb8aa3b, v174
	v_exp_f32_e32 v180, v180
	v_mul_f32_e32 v181, 0xbfb8aa3b, v178
	v_exp_f32_e32 v181, v181
	s_mov_b64 s[0:1], 0
	v_add_f32_e32 v180, 1.0, v180
	v_rcp_f32_e32 v180, v180
	v_add_f32_e32 v181, 1.0, v181
	v_rcp_f32_e32 v210, v181
	v_fmac_f32_e32 v142, v180, v209
	v_log_f32_e32 v181, v142
	v_fmac_f32_e32 v138, v210, v208
	v_mul_f32_e32 v142, 0xbfb8aa3b, v179
	v_log_f32_e32 v180, v138
	v_mul_f32_e32 v138, 0xbfb8aa3b, v175
	v_exp_f32_e32 v142, v142
	v_exp_f32_e32 v138, v138
	v_add_f32_e32 v142, 1.0, v142
	v_add_f32_e32 v138, 1.0, v138
	v_rcp_f32_e32 v142, v142
	v_rcp_f32_e32 v138, v138
	v_fmac_f32_e32 v139, v142, v206
	v_fmac_f32_e32 v143, v138, v207
	v_log_f32_e32 v210, v139
	v_mul_f32_e32 v138, 0xbfb8aa3b, v172
	v_mul_f32_e32 v139, 0xbfb8aa3b, v176
	v_exp_f32_e32 v138, v138
	v_exp_f32_e32 v139, v139
	v_log_f32_e32 v211, v143
	v_add_f32_e32 v138, 1.0, v138
	v_add_f32_e32 v139, 1.0, v139
	v_rcp_f32_e32 v138, v138
	v_rcp_f32_e32 v139, v139
	v_fmac_f32_e32 v144, v138, v205
	v_fmac_f32_e32 v140, v139, v204
	v_mul_f32_e32 v138, 0xbfb8aa3b, v173
	v_mul_f32_e32 v139, 0xbfb8aa3b, v177
	v_exp_f32_e32 v138, v138
	v_exp_f32_e32 v139, v139
	v_log_f32_e32 v213, v144
	v_log_f32_e32 v212, v140
	v_add_f32_e32 v138, 1.0, v138
	v_add_f32_e32 v139, 1.0, v139
	v_rcp_f32_e32 v138, v138
	v_rcp_f32_e32 v139, v139
	v_fmac_f32_e32 v145, v138, v201
	v_fmac_f32_e32 v141, v139, v200
	v_log_f32_e32 v215, v145
	v_log_f32_e32 v214, v141

; __device__ __forceinline__ unsigned cvt_pk_bf16(float lo, float hi) { unsigned r; asm volatile("v_cvt_pk_bf16_f32 %0, %1, %2" : "=v"(r) : "v"(lo), "v"(hi)); return r; }
; #define GAS __attribute__((address_space(1)))
; __device__ __forceinline__ float silu_f(float x) { return x * __builtin_amdgcn_rcpf(1.f + __builtin_amdgcn_exp2f(x * -1.4426950408889634f)); }
;     __device__ __forceinline__ void operator()(const pg8::f32x4 (&acc)[2][2][4][2], const pg8::Unit& u, int wr, int wc, int fr, int fq) const {
;     ...
;             for (int m = 0; m < 4; ++m) { GAS pg8::bf16_t* rowp = O + (size_t)(row0 + ai * 128 + m * 16) * PW + col0;
; #pragma unroll
;                 for (int bj = 0; bj < 2; ++bj) { pg8::f32x4 v0 = acc[ai][bj][m][0] * rsr[ai][m], v1 = acc[ai][bj][m][1] * rsr[ai][m];
;                     if (act == 1) {
; #pragma unroll
;                         for (int e = 0; e < 4; ++e) { v0[e] = silu_f(v0[e]); v1[e] = silu_f(v1[e]); } }
;                     else if (act == 2) {
; #pragma unroll
;                         for (int e = 0; e < 4; ++e) { const float s0 = __builtin_amdgcn_rcpf(1.f + __builtin_amdgcn_exp2f(v0[e] * -1.4426950408889634f)), s1 = __builtin_amdgcn_rcpf(1.f + __builtin_amdgcn_exp2f(v1[e] * -1.4426950408889634f));
;                             v0[e] = __builtin_amdgcn_logf(lbv[bj][0][e] + (1.f - lbv[bj][0][e]) * s0); v1[e] = __builtin_amdgcn_logf(lbv[bj][1][e] + (1.f - lbv[bj][1][e]) * s1);     } }
;                     pg8::u32x4 w; w.x = pg8::cvt_pk_bf16(v0[0], v0[1]); w.y = pg8::cvt_pk_bf16(v0[2], v0[3]); w.z = pg8::cvt_pk_bf16(v1[0], v1[1]); w.w = pg8::cvt_pk_bf16(v1[2], v1[3]);
;                     *(GAS pg8::u32x4*)(rowp + bj * 128) = w; } }
.LBB0_187:
	v_lshlrev_b64 v[138:139], 14, v[166:167]
	v_lshl_add_u64 v[138:139], s[12:13], 0, v[138:139]
	v_lshl_add_u64 v[144:145], v[170:171], 1, v[138:139]
	s_mov_b64 s[0:1], 0x2c0000
	v_lshl_add_u64 v[138:139], v[144:145], 0, s[0:1]
	v_add_co_u32_e32 v144, vcc, 0x2c0000, v144
	v_cvt_pk_bf16_f32 v140, v181, v211
	v_cvt_pk_bf16_f32 v141, v213, v215
	v_cvt_pk_bf16_f32 v142, v180, v210
	v_cvt_pk_bf16_f32 v143, v212, v214
	s_nop 1
	v_addc_co_u32_e32 v145, vcc, 0, v145, vcc
	global_store_dwordx4 v[144:145], v[140:143], off sc1
	v_mov_b32_e32 v172, v161
	v_mov_b32_e32 v173, v161
	v_mov_b32_e32 v144, v161
	v_mov_b32_e32 v145, v161
	v_pk_mul_f32 v[140:141], v[6:7], v[144:145]
	v_pk_mul_f32 v[142:143], v[4:5], v[172:173]
	v_pk_mul_f32 v[144:145], v[2:3], v[144:145]
	v_pk_mul_f32 v[170:171], v[0:1], v[172:173]
	s_cmp_gt_i32 s23, 1
	s_mov_b64 s[0:1], -1
	s_cbranch_scc0 .LBB0_189
	v_mul_f32_e32 v167, 0xbfb8aa3b, v142
	v_exp_f32_e32 v167, v167
	v_mul_f32_e32 v172, 0xbfb8aa3b, v170
	v_exp_f32_e32 v172, v172
	s_mov_b64 s[0:1], 0
	v_add_f32_e32 v167, 1.0, v167
	v_rcp_f32_e32 v167, v167
	v_add_f32_e32 v172, 1.0, v172
	v_rcp_f32_e32 v173, v172
	v_fmac_f32_e32 v134, v167, v203
	v_log_f32_e32 v172, v134
	v_fmac_f32_e32 v130, v173, v202
	v_mul_f32_e32 v134, 0xbfb8aa3b, v171
	v_log_f32_e32 v167, v130
	v_mul_f32_e32 v130, 0xbfb8aa3b, v143
	v_exp_f32_e32 v134, v134
	v_exp_f32_e32 v130, v130
	v_add_f32_e32 v134, 1.0, v134
	v_add_f32_e32 v130, 1.0, v130
	v_rcp_f32_e32 v134, v134
	v_rcp_f32_e32 v130, v130
	v_fmac_f32_e32 v131, v134, v198
	v_fmac_f32_e32 v135, v130, v199
	v_log_f32_e32 v173, v131
	v_mul_f32_e32 v130, 0xbfb8aa3b, v140
	v_mul_f32_e32 v131, 0xbfb8aa3b, v144
	v_exp_f32_e32 v130, v130
	v_exp_f32_e32 v131, v131
	v_log_f32_e32 v174, v135
	v_add_f32_e32 v130, 1.0, v130
	v_add_f32_e32 v131, 1.0, v131
	v_rcp_f32_e32 v130, v130
	v_rcp_f32_e32 v131, v131
	v_fmac_f32_e32 v136, v130, v197
	v_fmac_f32_e32 v132, v131, v196
	v_mul_f32_e32 v130, 0xbfb8aa3b, v141
	v_mul_f32_e32 v131, 0xbfb8aa3b, v145
	v_exp_f32_e32 v130, v130
	v_exp_f32_e32 v131, v131
	v_log_f32_e32 v176, v136
	v_log_f32_e32 v175, v132
	v_add_f32_e32 v130, 1.0, v130
	v_add_f32_e32 v131, 1.0, v131
	v_rcp_f32_e32 v130, v130
	v_rcp_f32_e32 v131, v131
	v_fmac_f32_e32 v137, v130, v195
	v_fmac_f32_e32 v133, v131, v112
	v_log_f32_e32 v178, v137
	v_log_f32_e32 v177, v133

; __device__ __forceinline__ unsigned cvt_pk_bf16(float lo, float hi) { unsigned r; asm volatile("v_cvt_pk_bf16_f32 %0, %1, %2" : "=v"(r) : "v"(lo), "v"(hi)); return r; }
; #define GAS __attribute__((address_space(1)))
;     __device__ __forceinline__ void operator()(const pg8::f32x4 (&acc)[2][2][4][2], const pg8::Unit& u, int wr, int wc, int fr, int fq) const {
;     ...
;             const int ncol = u.pn * 256 + 64 * wc + 8 * fq;
; #pragma unroll
;             for (int ai = 0; ai < 2; ++ai)
; #pragma unroll
;                 for (int m = 0; m < 4; ++m) { float ss = 0.f;
; #pragma unroll
;                     for (int bj = 0; bj < 2; ++bj)
; #pragma unroll
;                         for (int n = 0; n < 2; ++n) { const pg8::f32x4 v = acc[ai][bj][m][n] * rsr[ai][m]; ss += (v[0] * v[0] + v[1] * v[1]) + (v[2] * v[2] + v[3] * v[3]); }
;                     ss += __shfl_xor(ss, 16); ss += __shfl_xor(ss, 32);
;                     const float rs = rsqrtf(ss * (1.f / 64.f) + EPS);
;                     GAS pg8::bf16_t* rowp = O + (size_t)(row0 + ai * 128 + m * 16) * PW + ncol;
; #pragma unroll
;                     for (int bj = 0; bj < 2; ++bj) { const pg8::f32x4 v0 = acc[ai][bj][m][0] * (rs * rsr[ai][m]) * gv[bj][0], v1 = acc[ai][bj][m][1] * (rs * rsr[ai][m]) * gv[bj][1];
;                         pg8::u32x4 w; w.x = pg8::cvt_pk_bf16(v0[0], v0[1]); w.y = pg8::cvt_pk_bf16(v0[2], v0[3]); w.z = pg8::cvt_pk_bf16(v1[0], v1[1]); w.w = pg8::cvt_pk_bf16(v1[2], v1[3]);
;                         *(GAS pg8::u32x4*)(rowp + 32 * bj) = w; } }
;     ...
;                     pg8::u32x4 w; w.x = pg8::cvt_pk_bf16(v0[0], v0[1]); w.y = pg8::cvt_pk_bf16(v0[2], v0[3]); w.z = pg8::cvt_pk_bf16(v1[0], v1[1]); w.w = pg8::cvt_pk_bf16(v1[2], v1[3]);
;                     *(GAS pg8::u32x4*)(rowp + bj * 128) = w; } }
.LBB0_193:
	v_cvt_pk_bf16_f32 v130, v172, v174
	v_cvt_pk_bf16_f32 v131, v176, v178
	v_cvt_pk_bf16_f32 v132, v167, v173
	v_cvt_pk_bf16_f32 v133, v175, v177
	global_store_dwordx4 v[138:139], v[130:133], off offset:256 sc1
	s_and_b64 vcc, exec, s[30:31]
	s_cbranch_vccz .LBB0_88
.LBB0_194:
	v_and_b32_e32 v130, 64, v190
	v_add_u32_e32 v142, 64, v130
	s_waitcnt lgkmcnt(0)
	v_pk_mul_f32 v[130:131], v[128:129], v[168:169] op_sel_hi:[1,0]
	v_pk_mul_f32 v[132:133], v[126:127], v[168:169] op_sel_hi:[1,0]
	v_pk_mul_f32 v[130:131], v[130:131], v[130:131]
	v_pk_mul_f32 v[132:133], v[132:133], v[132:133]
	v_xor_b32_e32 v112, 16, v190
	v_pk_mov_b32 v[134:135], v[132:133], v[130:131] op_sel:[1,0]
	v_mov_b32_e32 v133, v131
	v_pk_add_f32 v[130:131], v[134:135], v[132:133]
	v_pk_mul_f32 v[132:133], v[124:125], v[168:169] op_sel_hi:[1,0]
	v_pk_mul_f32 v[134:135], v[122:123], v[168:169] op_sel_hi:[1,0]
	v_pk_mul_f32 v[132:133], v[132:133], v[132:133]
	v_pk_mul_f32 v[134:135], v[134:135], v[134:135]
	v_cmp_lt_i32_e32 vcc, v112, v142
	v_pk_mov_b32 v[136:137], v[134:135], v[132:133] op_sel:[1,0]
	v_mov_b32_e32 v135, v133
	v_cndmask_b32_e32 v112, v190, v112, vcc
	v_pk_add_f32 v[132:133], v[136:137], v[134:135]
	v_pk_mul_f32 v[136:137], v[118:119], v[168:169] op_sel_hi:[1,0]
	v_lshlrev_b32_e32 v174, 2, v112
	v_pk_mul_f32 v[134:135], v[120:121], v[168:169] op_sel_hi:[1,0]
	v_mul_f32_e32 v112, v136, v136
	v_pk_fma_f32 v[136:137], v[136:137], v[136:137], v[112:113] op_sel_hi:[1,1,0]
	v_mul_f32_e32 v112, v134, v134
	v_pk_add_f32 v[130:131], v[130:131], v[130:131] op_sel_hi:[0,1]
	v_pk_add_f32 v[132:133], v[132:133], v[132:133] op_sel_hi:[0,1]
	v_pk_fma_f32 v[134:135], v[134:135], v[134:135], v[112:113] op_sel_hi:[1,1,0]
	v_pk_mul_f32 v[138:139], v[116:117], v[168:169] op_sel_hi:[1,0]
	v_pk_mul_f32 v[140:141], v[114:115], v[168:169] op_sel_hi:[1,0]
	v_mul_f32_e32 v130, v138, v138
	v_mul_f32_e32 v136, v140, v140
	v_mul_f32_e32 v134, v141, v141
	v_mul_f32_e32 v132, v139, v139
	v_pk_add_f32 v[134:135], v[136:137], v[134:135]
	v_pk_add_f32 v[130:131], v[130:131], v[132:133]
	s_lshl_b32 s0, s28, 4
	v_pk_add_f32 v[130:131], v[134:135], v[130:131]
	s_and_b32 s0, s0, 0x100
	v_add_f32_e32 v112, v130, v131
	ds_bpermute_b32 v130, v174, v112
	v_xor_b32_e32 v131, 32, v190
	v_cmp_lt_i32_e32 vcc, v131, v142
	s_waitcnt lgkmcnt(0)
	v_add_f32_e32 v112, v112, v130
	v_cndmask_b32_e32 v131, v190, v131, vcc
	v_lshlrev_b32_e32 v175, 2, v131
	ds_bpermute_b32 v130, v175, v112
	v_add_u32_e32 v131, s0, v185
	ds_read_b128 v[142:145], v131
	ds_read_b128 v[138:141], v131 offset:16
	s_mov_b64 s[0:1], 0x200000
	s_waitcnt lgkmcnt(0)
	v_add_f32_e32 v112, v112, v130
	v_fmamk_f32 v112, v112, 0x3c800000, v188
	v_mul_f32_e32 v130, 0x4b800000, v112
	v_cmp_gt_f32_e32 vcc, s92, v112
	s_nop 1
	v_cndmask_b32_e32 v112, v112, v130, vcc
	v_rsq_f32_e32 v167, v112
	v_or_b32_e32 v112, s21, v184
	v_lshlrev_b64 v[172:173], 1, v[112:113]
	ds_read_b128 v[134:137], v131 offset:128
	ds_read_b128 v[130:133], v131 offset:144
	v_mul_f32_e32 v170, 0x45800000, v167
	v_cndmask_b32_e32 v176, v167, v170, vcc
	v_ashrrev_i32_e32 v167, 31, v166
	v_lshlrev_b64 v[170:171], 14, v[166:167]
	v_mul_f32_e32 v112, v168, v176
	v_lshl_add_u64 v[170:171], s[12:13], 0, v[170:171]
	v_pk_mul_f32 v[126:127], v[126:127], v[112:113] op_sel_hi:[1,0]
	v_pk_mul_f32 v[122:123], v[122:123], v[112:113] op_sel_hi:[1,0]
	v_pk_mul_f32 v[124:125], v[124:125], v[112:113] op_sel_hi:[1,0]
	v_lshl_add_u64 v[170:171], v[170:171], 0, v[172:173]
	v_pk_mul_f32 v[128:129], v[128:129], v[112:113] op_sel_hi:[1,0]
	v_pk_mul_f32 v[126:127], v[142:143], v[126:127]
	v_pk_mul_f32 v[176:177], v[140:141], v[124:125]
	v_pk_mul_f32 v[124:125], v[138:139], v[122:123]
	v_cvt_pk_bf16_f32 v122, v126, v127
	v_pk_mul_f32 v[128:129], v[144:145], v[128:129]
	v_pk_mul_f32 v[118:119], v[118:119], v[112:113] op_sel_hi:[1,0]
	v_cvt_pk_bf16_f32 v123, v128, v129
	v_cvt_pk_bf16_f32 v124, v124, v125
	v_cvt_pk_bf16_f32 v125, v176, v177
	global_store_dwordx4 v[170:171], v[122:125], off sc1
	v_pk_mul_f32 v[120:121], v[120:121], v[112:113] op_sel_hi:[1,0]
	v_pk_mul_f32 v[114:115], v[114:115], v[112:113] op_sel_hi:[1,0]
	v_mov_b32_e32 v122, v169
	v_pk_mul_f32 v[124:125], v[110:111], v[122:123] op_sel_hi:[1,0]
	v_pk_mul_f32 v[126:127], v[108:109], v[122:123] op_sel_hi:[1,0]
	v_pk_mul_f32 v[124:125], v[124:125], v[124:125]
	v_pk_mul_f32 v[126:127], v[126:127], v[126:127]
	v_pk_mul_f32 v[178:179], v[98:99], v[122:123] op_sel_hi:[1,0]
	v_pk_mov_b32 v[128:129], v[126:127], v[124:125] op_sel:[1,0]
	v_mov_b32_e32 v127, v125
	v_pk_add_f32 v[124:125], v[128:129], v[126:127]
	v_pk_mul_f32 v[126:127], v[106:107], v[122:123] op_sel_hi:[1,0]
	v_pk_mul_f32 v[128:129], v[104:105], v[122:123] op_sel_hi:[1,0]
	v_pk_mul_f32 v[126:127], v[126:127], v[126:127]
	v_pk_mul_f32 v[128:129], v[128:129], v[128:129]
	v_pk_add_f32 v[124:125], v[124:125], v[124:125] op_sel_hi:[0,1]
	v_pk_mov_b32 v[176:177], v[128:129], v[126:127] op_sel:[1,0]
	v_mov_b32_e32 v129, v127
	v_pk_add_f32 v[126:127], v[176:177], v[128:129]
	v_pk_mul_f32 v[176:177], v[100:101], v[122:123] op_sel_hi:[1,0]
	v_pk_mul_f32 v[128:129], v[102:103], v[122:123] op_sel_hi:[1,0]
	v_mul_f32_e32 v124, v176, v176
	v_pk_fma_f32 v[176:177], v[176:177], v[176:177], v[124:125] op_sel_hi:[1,1,0]
	v_mul_f32_e32 v124, v128, v128
	v_pk_add_f32 v[126:127], v[126:127], v[126:127] op_sel_hi:[0,1]
	v_pk_fma_f32 v[128:129], v[128:129], v[128:129], v[124:125] op_sel_hi:[1,1,0]
	v_pk_mul_f32 v[122:123], v[96:97], v[122:123] op_sel_hi:[1,0]
	v_mul_f32_e32 v124, v178, v178
	v_mul_f32_e32 v176, v122, v122
	v_mul_f32_e32 v128, v123, v123
	v_mul_f32_e32 v126, v179, v179
	v_pk_add_f32 v[122:123], v[176:177], v[128:129]
	v_pk_add_f32 v[124:125], v[124:125], v[126:127]
	v_pk_mul_f32 v[116:117], v[116:117], v[112:113] op_sel_hi:[1,0]
	v_pk_add_f32 v[122:123], v[122:123], v[124:125]
	s_waitcnt lgkmcnt(0)
; __device__ __forceinline__ unsigned cvt_pk_bf16(float lo, float hi) { unsigned r; asm volatile("v_cvt_pk_bf16_f32 %0, %1, %2" : "=v"(r) : "v"(lo), "v"(hi)); return r; }
; #define GAS __attribute__((address_space(1)))
;     __device__ __forceinline__ void operator()(const pg8::f32x4 (&acc)[2][2][4][2], const pg8::Unit& u, int wr, int wc, int fr, int fq) const {
;     ...
;                 for (int m = 0; m < 4; ++m) { float ss = 0.f;
; #pragma unroll
;                     for (int bj = 0; bj < 2; ++bj)
; #pragma unroll
;                         for (int n = 0; n < 2; ++n) { const pg8::f32x4 v = acc[ai][bj][m][n] * rsr[ai][m]; ss += (v[0] * v[0] + v[1] * v[1]) + (v[2] * v[2] + v[3] * v[3]); }
;                     ss += __shfl_xor(ss, 16); ss += __shfl_xor(ss, 32);
;                     const float rs = rsqrtf(ss * (1.f / 64.f) + EPS);
;                     GAS pg8::bf16_t* rowp = O + (size_t)(row0 + ai * 128 + m * 16) * PW + ncol;
; #pragma unroll
;                     for (int bj = 0; bj < 2; ++bj) { const pg8::f32x4 v0 = acc[ai][bj][m][0] * (rs * rsr[ai][m]) * gv[bj][0], v1 = acc[ai][bj][m][1] * (rs * rsr[ai][m]) * gv[bj][1];
;                         pg8::u32x4 w; w.x = pg8::cvt_pk_bf16(v0[0], v0[1]); w.y = pg8::cvt_pk_bf16(v0[2], v0[3]); w.z = pg8::cvt_pk_bf16(v1[0], v1[1]); w.w = pg8::cvt_pk_bf16(v1[2], v1[3]);
;                         *(GAS pg8::u32x4*)(rowp + 32 * bj) = w; } }
	v_pk_mul_f32 v[118:119], v[134:135], v[118:119]
	v_add_f32_e32 v122, v122, v123
	ds_bpermute_b32 v123, v174, v122
	v_pk_mul_f32 v[120:121], v[136:137], v[120:121]
	s_waitcnt lgkmcnt(0)
	v_add_f32_e32 v112, v122, v123
	ds_bpermute_b32 v124, v175, v112
	v_pk_mul_f32 v[122:123], v[132:133], v[116:117]
	v_pk_mul_f32 v[116:117], v[130:131], v[114:115]
	v_cvt_pk_bf16_f32 v114, v118, v119
	v_cvt_pk_bf16_f32 v115, v120, v121
	s_waitcnt lgkmcnt(0)
	v_add_f32_e32 v112, v112, v124
	v_fmamk_f32 v112, v112, 0x3c800000, v188
	v_mul_f32_e32 v118, 0x4b800000, v112
	v_cmp_gt_f32_e32 vcc, s92, v112
	v_cvt_pk_bf16_f32 v116, v116, v117
	v_cvt_pk_bf16_f32 v117, v122, v123
	global_store_dwordx4 v[170:171], v[114:117], off offset:64 sc1
	s_nop 0
	v_cndmask_b32_e32 v112, v112, v118, vcc
	v_rsq_f32_e32 v112, v112
	v_pk_mul_f32 v[118:119], v[80:81], v[164:165] op_sel_hi:[1,0]
	v_mul_f32_e32 v114, 0x45800000, v112
	v_cndmask_b32_e32 v112, v112, v114, vcc
	v_or_b32_e32 v114, 16, v166
	v_ashrrev_i32_e32 v115, 31, v114
	v_mul_f32_e32 v112, v169, v112
	v_lshlrev_b64 v[114:115], 14, v[114:115]
	v_pk_mul_f32 v[104:105], v[104:105], v[112:113] op_sel_hi:[1,0]
	v_pk_mul_f32 v[106:107], v[106:107], v[112:113] op_sel_hi:[1,0]
	v_lshl_add_u64 v[114:115], s[12:13], 0, v[114:115]
	v_pk_mul_f32 v[108:109], v[108:109], v[112:113] op_sel_hi:[1,0]
	v_pk_mul_f32 v[110:111], v[110:111], v[112:113] op_sel_hi:[1,0]
	v_pk_mul_f32 v[116:117], v[140:141], v[106:107]
	v_pk_mul_f32 v[106:107], v[138:139], v[104:105]
	v_lshl_add_u64 v[114:115], v[114:115], 0, v[172:173]
	v_pk_mul_f32 v[110:111], v[144:145], v[110:111]
	v_pk_mul_f32 v[108:109], v[142:143], v[108:109]
	v_pk_mul_f32 v[100:101], v[100:101], v[112:113] op_sel_hi:[1,0]
	v_cvt_pk_bf16_f32 v104, v108, v109
	v_cvt_pk_bf16_f32 v105, v110, v111
	v_cvt_pk_bf16_f32 v106, v106, v107
	v_cvt_pk_bf16_f32 v107, v116, v117
	global_store_dwordx4 v[114:115], v[104:107], off sc1
	v_pk_mul_f32 v[116:117], v[82:83], v[164:165] op_sel_hi:[1,0]
	v_pk_mul_f32 v[100:101], v[134:135], v[100:101]
	v_pk_mul_f32 v[104:105], v[94:95], v[164:165] op_sel_hi:[1,0]
	v_pk_mul_f32 v[106:107], v[92:93], v[164:165] op_sel_hi:[1,0]
	v_pk_mul_f32 v[104:105], v[104:105], v[104:105]
	v_pk_mul_f32 v[106:107], v[106:107], v[106:107]
	v_pk_mul_f32 v[96:97], v[96:97], v[112:113] op_sel_hi:[1,0]
	v_pk_mov_b32 v[108:109], v[106:107], v[104:105] op_sel:[1,0]
	v_mov_b32_e32 v107, v105
	v_pk_add_f32 v[104:105], v[108:109], v[106:107]
	v_pk_mul_f32 v[106:107], v[90:91], v[164:165] op_sel_hi:[1,0]
	v_pk_mul_f32 v[108:109], v[88:89], v[164:165] op_sel_hi:[1,0]
	v_pk_mul_f32 v[106:107], v[106:107], v[106:107]
	v_pk_mul_f32 v[108:109], v[108:109], v[108:109]
	v_pk_add_f32 v[104:105], v[104:105], v[104:105] op_sel_hi:[0,1]
	v_pk_mov_b32 v[110:111], v[108:109], v[106:107] op_sel:[1,0]
	v_mov_b32_e32 v109, v107
	v_pk_add_f32 v[106:107], v[110:111], v[108:109]
	v_pk_mul_f32 v[110:111], v[84:85], v[164:165] op_sel_hi:[1,0]
	v_pk_mul_f32 v[108:109], v[86:87], v[164:165] op_sel_hi:[1,0]
	v_mul_f32_e32 v104, v110, v110
	v_pk_fma_f32 v[110:111], v[110:111], v[110:111], v[104:105] op_sel_hi:[1,1,0]
	v_mul_f32_e32 v104, v108, v108
	v_pk_add_f32 v[106:107], v[106:107], v[106:107] op_sel_hi:[0,1]
	v_pk_fma_f32 v[108:109], v[108:109], v[108:109], v[104:105] op_sel_hi:[1,1,0]
	v_mul_f32_e32 v110, v118, v118
	v_mul_f32_e32 v108, v119, v119
	v_mul_f32_e32 v104, v116, v116
	v_mul_f32_e32 v106, v117, v117
	v_pk_add_f32 v[108:109], v[110:111], v[108:109]
	v_pk_add_f32 v[104:105], v[104:105], v[106:107]
	v_pk_mul_f32 v[98:99], v[98:99], v[112:113] op_sel_hi:[1,0]
	v_pk_add_f32 v[104:105], v[108:109], v[104:105]
	v_pk_mul_f32 v[102:103], v[102:103], v[112:113] op_sel_hi:[1,0]
	v_add_f32_e32 v104, v104, v105
	ds_bpermute_b32 v105, v174, v104
	v_pk_mul_f32 v[102:103], v[136:137], v[102:103]
	s_waitcnt lgkmcnt(0)
	v_add_f32_e32 v106, v104, v105
	ds_bpermute_b32 v107, v175, v106
	v_pk_mul_f32 v[104:105], v[132:133], v[98:99]
	v_pk_mul_f32 v[98:99], v[130:131], v[96:97]
	v_cvt_pk_bf16_f32 v96, v100, v101
	v_cvt_pk_bf16_f32 v97, v102, v103
	s_waitcnt lgkmcnt(0)
	v_add_f32_e32 v100, v106, v107
	v_fmamk_f32 v100, v100, 0x3c800000, v188
	v_mul_f32_e32 v101, 0x4b800000, v100
	v_cmp_gt_f32_e32 vcc, s92, v100
	v_cvt_pk_bf16_f32 v98, v98, v99
	v_cvt_pk_bf16_f32 v99, v104, v105
	global_store_dwordx4 v[114:115], v[96:99], off offset:64 sc1
	s_nop 0
	v_cndmask_b32_e32 v100, v100, v101, vcc
	v_rsq_f32_e32 v100, v100
	s_nop 0
	v_mul_f32_e32 v96, 0x45800000, v100
	v_cndmask_b32_e32 v98, v100, v96, vcc
	v_or_b32_e32 v96, 32, v166
	v_ashrrev_i32_e32 v97, 31, v96
	v_lshlrev_b64 v[96:97], 14, v[96:97]
	v_mul_f32_e32 v98, v164, v98
	v_lshl_add_u64 v[96:97], s[12:13], 0, v[96:97]
	v_pk_mul_f32 v[92:93], v[92:93], v[98:99] op_sel_hi:[1,0]
	v_pk_mul_f32 v[88:89], v[88:89], v[98:99] op_sel_hi:[1,0]
	v_pk_mul_f32 v[90:91], v[90:91], v[98:99] op_sel_hi:[1,0]
	v_lshl_add_u64 v[96:97], v[96:97], 0, v[172:173]
	v_pk_mul_f32 v[94:95], v[94:95], v[98:99] op_sel_hi:[1,0]
	v_pk_mul_f32 v[92:93], v[142:143], v[92:93]
	v_pk_mul_f32 v[100:101], v[140:141], v[90:91]
	v_pk_mul_f32 v[90:91], v[138:139], v[88:89]
	v_cvt_pk_bf16_f32 v88, v92, v93
	v_pk_mul_f32 v[94:95], v[144:145], v[94:95]
	v_pk_mul_f32 v[84:85], v[84:85], v[98:99] op_sel_hi:[1,0]
	v_cvt_pk_bf16_f32 v89, v94, v95
	v_cvt_pk_bf16_f32 v90, v90, v91
	v_cvt_pk_bf16_f32 v91, v100, v101
	global_store_dwordx4 v[96:97], v[88:91], off sc1
	v_pk_mul_f32 v[84:85], v[134:135], v[84:85]
	v_pk_mul_f32 v[80:81], v[80:81], v[98:99] op_sel_hi:[1,0]
	v_mov_b32_e32 v88, v165
	v_pk_mul_f32 v[90:91], v[78:79], v[88:89] op_sel_hi:[1,0]
	v_pk_mul_f32 v[92:93], v[76:77], v[88:89] op_sel_hi:[1,0]
; __device__ __forceinline__ unsigned cvt_pk_bf16(float lo, float hi) { unsigned r; asm volatile("v_cvt_pk_bf16_f32 %0, %1, %2" : "=v"(r) : "v"(lo), "v"(hi)); return r; }
; #define GAS __attribute__((address_space(1)))
;     __device__ __forceinline__ void operator()(const pg8::f32x4 (&acc)[2][2][4][2], const pg8::Unit& u, int wr, int wc, int fr, int fq) const {
;     ...
;                 for (int m = 0; m < 4; ++m) { float ss = 0.f;
; #pragma unroll
;                     for (int bj = 0; bj < 2; ++bj)
; #pragma unroll
;                         for (int n = 0; n < 2; ++n) { const pg8::f32x4 v = acc[ai][bj][m][n] * rsr[ai][m]; ss += (v[0] * v[0] + v[1] * v[1]) + (v[2] * v[2] + v[3] * v[3]); }
;                     ss += __shfl_xor(ss, 16); ss += __shfl_xor(ss, 32);
;                     const float rs = rsqrtf(ss * (1.f / 64.f) + EPS);
;                     GAS pg8::bf16_t* rowp = O + (size_t)(row0 + ai * 128 + m * 16) * PW + ncol;
; #pragma unroll
;                     for (int bj = 0; bj < 2; ++bj) { const pg8::f32x4 v0 = acc[ai][bj][m][0] * (rs * rsr[ai][m]) * gv[bj][0], v1 = acc[ai][bj][m][1] * (rs * rsr[ai][m]) * gv[bj][1];
;                         pg8::u32x4 w; w.x = pg8::cvt_pk_bf16(v0[0], v0[1]); w.y = pg8::cvt_pk_bf16(v0[2], v0[3]); w.z = pg8::cvt_pk_bf16(v1[0], v1[1]); w.w = pg8::cvt_pk_bf16(v1[2], v1[3]);
;                         *(GAS pg8::u32x4*)(rowp + 32 * bj) = w; } }
	v_pk_mul_f32 v[90:91], v[90:91], v[90:91]
	v_pk_mul_f32 v[92:93], v[92:93], v[92:93]
	v_pk_mul_f32 v[102:103], v[66:67], v[88:89] op_sel_hi:[1,0]
	v_pk_mov_b32 v[94:95], v[92:93], v[90:91] op_sel:[1,0]
	v_mov_b32_e32 v93, v91
	v_pk_add_f32 v[90:91], v[94:95], v[92:93]
	v_pk_mul_f32 v[92:93], v[74:75], v[88:89] op_sel_hi:[1,0]
	v_pk_mul_f32 v[94:95], v[72:73], v[88:89] op_sel_hi:[1,0]
	v_pk_mul_f32 v[92:93], v[92:93], v[92:93]
	v_pk_mul_f32 v[94:95], v[94:95], v[94:95]
	v_pk_add_f32 v[90:91], v[90:91], v[90:91] op_sel_hi:[0,1]
	v_pk_mov_b32 v[100:101], v[94:95], v[92:93] op_sel:[1,0]
	v_mov_b32_e32 v95, v93
	v_pk_add_f32 v[92:93], v[100:101], v[94:95]
	v_pk_mul_f32 v[100:101], v[68:69], v[88:89] op_sel_hi:[1,0]
	v_pk_mul_f32 v[94:95], v[70:71], v[88:89] op_sel_hi:[1,0]
	v_mul_f32_e32 v90, v100, v100
	v_pk_fma_f32 v[100:101], v[100:101], v[100:101], v[90:91] op_sel_hi:[1,1,0]
	v_mul_f32_e32 v90, v94, v94
	v_pk_add_f32 v[92:93], v[92:93], v[92:93] op_sel_hi:[0,1]
	v_pk_fma_f32 v[94:95], v[94:95], v[94:95], v[90:91] op_sel_hi:[1,1,0]
	v_pk_mul_f32 v[88:89], v[64:65], v[88:89] op_sel_hi:[1,0]
	v_mul_f32_e32 v90, v102, v102
	v_mul_f32_e32 v100, v88, v88
	v_mul_f32_e32 v94, v89, v89
	v_mul_f32_e32 v92, v103, v103
	v_pk_add_f32 v[88:89], v[100:101], v[94:95]
	v_pk_add_f32 v[90:91], v[90:91], v[92:93]
	v_pk_mul_f32 v[82:83], v[82:83], v[98:99] op_sel_hi:[1,0]
	v_pk_add_f32 v[88:89], v[88:89], v[90:91]
	v_pk_mul_f32 v[86:87], v[86:87], v[98:99] op_sel_hi:[1,0]
	v_add_f32_e32 v88, v88, v89
	ds_bpermute_b32 v89, v174, v88
	v_pk_mul_f32 v[86:87], v[136:137], v[86:87]
	s_waitcnt lgkmcnt(0)
	v_add_f32_e32 v90, v88, v89
	ds_bpermute_b32 v91, v175, v90
	v_pk_mul_f32 v[88:89], v[132:133], v[82:83]
	v_pk_mul_f32 v[82:83], v[130:131], v[80:81]
	v_cvt_pk_bf16_f32 v80, v84, v85
	v_cvt_pk_bf16_f32 v81, v86, v87
	s_waitcnt lgkmcnt(0)
	v_add_f32_e32 v84, v90, v91
	v_fmamk_f32 v84, v84, 0x3c800000, v188
	v_mul_f32_e32 v85, 0x4b800000, v84
	v_cmp_gt_f32_e32 vcc, s92, v84
	v_cvt_pk_bf16_f32 v82, v82, v83
	v_cvt_pk_bf16_f32 v83, v88, v89
	global_store_dwordx4 v[96:97], v[80:83], off offset:64 sc1
	v_pk_mul_f32 v[86:87], v[44:45], v[162:163] op_sel_hi:[1,0]
	v_cndmask_b32_e32 v84, v84, v85, vcc
	v_rsq_f32_e32 v84, v84
	s_nop 0
	v_mul_f32_e32 v80, 0x45800000, v84
	v_cndmask_b32_e32 v82, v84, v80, vcc
	v_or_b32_e32 v80, 48, v166
	v_ashrrev_i32_e32 v81, 31, v80
	v_mul_f32_e32 v82, v165, v82
	v_lshlrev_b64 v[80:81], 14, v[80:81]
	v_pk_mul_f32 v[72:73], v[72:73], v[82:83] op_sel_hi:[1,0]
	v_pk_mul_f32 v[74:75], v[74:75], v[82:83] op_sel_hi:[1,0]
	v_lshl_add_u64 v[80:81], s[12:13], 0, v[80:81]
	v_pk_mul_f32 v[76:77], v[76:77], v[82:83] op_sel_hi:[1,0]
	v_pk_mul_f32 v[78:79], v[78:79], v[82:83] op_sel_hi:[1,0]
	v_pk_mul_f32 v[84:85], v[140:141], v[74:75]
	v_pk_mul_f32 v[74:75], v[138:139], v[72:73]
	v_lshl_add_u64 v[80:81], v[80:81], 0, v[172:173]
	v_pk_mul_f32 v[78:79], v[144:145], v[78:79]
	v_pk_mul_f32 v[76:77], v[142:143], v[76:77]
	v_pk_mul_f32 v[68:69], v[68:69], v[82:83] op_sel_hi:[1,0]
	v_cvt_pk_bf16_f32 v72, v76, v77
	v_cvt_pk_bf16_f32 v73, v78, v79
	v_cvt_pk_bf16_f32 v74, v74, v75
	v_cvt_pk_bf16_f32 v75, v84, v85
	global_store_dwordx4 v[80:81], v[72:75], off sc1
	v_pk_mul_f32 v[84:85], v[46:47], v[162:163] op_sel_hi:[1,0]
	v_pk_mul_f32 v[68:69], v[134:135], v[68:69]
	v_pk_mul_f32 v[72:73], v[62:63], v[162:163] op_sel_hi:[1,0]
	v_pk_mul_f32 v[74:75], v[60:61], v[162:163] op_sel_hi:[1,0]
	v_pk_mul_f32 v[72:73], v[72:73], v[72:73]
	v_pk_mul_f32 v[74:75], v[74:75], v[74:75]
	v_pk_mul_f32 v[64:65], v[64:65], v[82:83] op_sel_hi:[1,0]
	v_pk_mov_b32 v[76:77], v[74:75], v[72:73] op_sel:[1,0]
	v_mov_b32_e32 v75, v73
	v_pk_add_f32 v[72:73], v[76:77], v[74:75]
	v_pk_mul_f32 v[74:75], v[58:59], v[162:163] op_sel_hi:[1,0]
	v_pk_mul_f32 v[76:77], v[56:57], v[162:163] op_sel_hi:[1,0]
	v_pk_mul_f32 v[74:75], v[74:75], v[74:75]
	v_pk_mul_f32 v[76:77], v[76:77], v[76:77]
	v_pk_add_f32 v[72:73], v[72:73], v[72:73] op_sel_hi:[0,1]
	v_pk_mov_b32 v[78:79], v[76:77], v[74:75] op_sel:[1,0]
	v_mov_b32_e32 v77, v75
	v_pk_add_f32 v[74:75], v[78:79], v[76:77]
	v_pk_mul_f32 v[78:79], v[52:53], v[162:163] op_sel_hi:[1,0]
	v_pk_mul_f32 v[76:77], v[54:55], v[162:163] op_sel_hi:[1,0]
	v_mul_f32_e32 v72, v78, v78
	v_pk_fma_f32 v[78:79], v[78:79], v[78:79], v[72:73] op_sel_hi:[1,1,0]
	v_mul_f32_e32 v72, v76, v76
	v_pk_add_f32 v[74:75], v[74:75], v[74:75] op_sel_hi:[0,1]
	v_pk_fma_f32 v[76:77], v[76:77], v[76:77], v[72:73] op_sel_hi:[1,1,0]
	v_mul_f32_e32 v78, v86, v86
	v_mul_f32_e32 v76, v87, v87
	v_mul_f32_e32 v72, v84, v84
	v_mul_f32_e32 v74, v85, v85
	v_pk_add_f32 v[76:77], v[78:79], v[76:77]
	v_pk_add_f32 v[72:73], v[72:73], v[74:75]
	v_pk_mul_f32 v[66:67], v[66:67], v[82:83] op_sel_hi:[1,0]
	v_pk_add_f32 v[72:73], v[76:77], v[72:73]
	v_pk_mul_f32 v[70:71], v[70:71], v[82:83] op_sel_hi:[1,0]
	v_add_f32_e32 v72, v72, v73
	ds_bpermute_b32 v73, v174, v72
	v_pk_mul_f32 v[70:71], v[136:137], v[70:71]
	s_waitcnt lgkmcnt(0)
	v_add_f32_e32 v74, v72, v73
	ds_bpermute_b32 v75, v175, v74
	v_pk_mul_f32 v[72:73], v[132:133], v[66:67]
	v_pk_mul_f32 v[66:67], v[130:131], v[64:65]
	v_cvt_pk_bf16_f32 v64, v68, v69
	v_cvt_pk_bf16_f32 v65, v70, v71
	s_waitcnt lgkmcnt(0)
; __device__ __forceinline__ unsigned cvt_pk_bf16(float lo, float hi) { unsigned r; asm volatile("v_cvt_pk_bf16_f32 %0, %1, %2" : "=v"(r) : "v"(lo), "v"(hi)); return r; }
; #define GAS __attribute__((address_space(1)))
;     __device__ __forceinline__ void operator()(const pg8::f32x4 (&acc)[2][2][4][2], const pg8::Unit& u, int wr, int wc, int fr, int fq) const {
;     ...
;                 for (int m = 0; m < 4; ++m) { float ss = 0.f;
; #pragma unroll
;                     for (int bj = 0; bj < 2; ++bj)
; #pragma unroll
;                         for (int n = 0; n < 2; ++n) { const pg8::f32x4 v = acc[ai][bj][m][n] * rsr[ai][m]; ss += (v[0] * v[0] + v[1] * v[1]) + (v[2] * v[2] + v[3] * v[3]); }
;                     ss += __shfl_xor(ss, 16); ss += __shfl_xor(ss, 32);
;                     const float rs = rsqrtf(ss * (1.f / 64.f) + EPS);
;                     GAS pg8::bf16_t* rowp = O + (size_t)(row0 + ai * 128 + m * 16) * PW + ncol;
; #pragma unroll
;                     for (int bj = 0; bj < 2; ++bj) { const pg8::f32x4 v0 = acc[ai][bj][m][0] * (rs * rsr[ai][m]) * gv[bj][0], v1 = acc[ai][bj][m][1] * (rs * rsr[ai][m]) * gv[bj][1];
;                         pg8::u32x4 w; w.x = pg8::cvt_pk_bf16(v0[0], v0[1]); w.y = pg8::cvt_pk_bf16(v0[2], v0[3]); w.z = pg8::cvt_pk_bf16(v1[0], v1[1]); w.w = pg8::cvt_pk_bf16(v1[2], v1[3]);
;                         *(GAS pg8::u32x4*)(rowp + 32 * bj) = w; } }
	v_add_f32_e32 v68, v74, v75
	v_fmamk_f32 v68, v68, 0x3c800000, v188
	v_mul_f32_e32 v69, 0x4b800000, v68
	v_cmp_gt_f32_e32 vcc, s92, v68
	v_cvt_pk_bf16_f32 v66, v66, v67
	v_cvt_pk_bf16_f32 v67, v72, v73
	global_store_dwordx4 v[80:81], v[64:67], off offset:64 sc1
	s_nop 0
	v_cndmask_b32_e32 v68, v68, v69, vcc
	v_rsq_f32_e32 v68, v68
	s_nop 0
	v_mul_f32_e32 v64, 0x45800000, v68
	v_cndmask_b32_e32 v66, v68, v64, vcc
	v_mul_f32_e32 v66, v162, v66
	v_pk_mul_f32 v[60:61], v[60:61], v[66:67] op_sel_hi:[1,0]
	v_lshl_add_u64 v[64:65], v[170:171], 0, s[0:1]
	v_pk_mul_f32 v[60:61], v[142:143], v[60:61]
	v_pk_mul_f32 v[56:57], v[56:57], v[66:67] op_sel_hi:[1,0]
	v_pk_mul_f32 v[58:59], v[58:59], v[66:67] op_sel_hi:[1,0]
	s_mov_b32 s0, 0x200000
	v_pk_mul_f32 v[68:69], v[140:141], v[58:59]
	v_pk_mul_f32 v[58:59], v[138:139], v[56:57]
	v_cvt_pk_bf16_f32 v56, v60, v61
	v_add_co_u32_e32 v60, vcc, s0, v170
	v_pk_mul_f32 v[62:63], v[62:63], v[66:67] op_sel_hi:[1,0]
	s_nop 0
	v_addc_co_u32_e32 v61, vcc, 0, v171, vcc
	v_pk_mul_f32 v[62:63], v[144:145], v[62:63]
	v_pk_mul_f32 v[52:53], v[52:53], v[66:67] op_sel_hi:[1,0]
	v_cvt_pk_bf16_f32 v57, v62, v63
	v_cvt_pk_bf16_f32 v58, v58, v59
	v_cvt_pk_bf16_f32 v59, v68, v69
	global_store_dwordx4 v[60:61], v[56:59], off sc1
	v_pk_mul_f32 v[52:53], v[134:135], v[52:53]
	v_pk_mul_f32 v[44:45], v[44:45], v[66:67] op_sel_hi:[1,0]
	v_mov_b32_e32 v56, v163
	v_pk_mul_f32 v[58:59], v[50:51], v[56:57] op_sel_hi:[1,0]
	v_pk_mul_f32 v[60:61], v[48:49], v[56:57] op_sel_hi:[1,0]
	v_pk_mul_f32 v[58:59], v[58:59], v[58:59]
	v_pk_mul_f32 v[60:61], v[60:61], v[60:61]
	v_pk_mul_f32 v[70:71], v[30:31], v[56:57] op_sel_hi:[1,0]
	v_pk_mov_b32 v[62:63], v[60:61], v[58:59] op_sel:[1,0]
	v_mov_b32_e32 v61, v59
	v_pk_add_f32 v[58:59], v[62:63], v[60:61]
	v_pk_mul_f32 v[60:61], v[42:43], v[56:57] op_sel_hi:[1,0]
	v_pk_mul_f32 v[62:63], v[40:41], v[56:57] op_sel_hi:[1,0]
	v_pk_mul_f32 v[60:61], v[60:61], v[60:61]
	v_pk_mul_f32 v[62:63], v[62:63], v[62:63]
	v_pk_add_f32 v[58:59], v[58:59], v[58:59] op_sel_hi:[0,1]
	v_pk_mov_b32 v[68:69], v[62:63], v[60:61] op_sel:[1,0]
	v_mov_b32_e32 v63, v61
	v_pk_add_f32 v[60:61], v[68:69], v[62:63]
	v_pk_mul_f32 v[68:69], v[36:37], v[56:57] op_sel_hi:[1,0]
	v_pk_mul_f32 v[62:63], v[38:39], v[56:57] op_sel_hi:[1,0]
	v_mul_f32_e32 v58, v68, v68
	v_pk_fma_f32 v[68:69], v[68:69], v[68:69], v[58:59] op_sel_hi:[1,1,0]
	v_mul_f32_e32 v58, v62, v62
	v_pk_add_f32 v[60:61], v[60:61], v[60:61] op_sel_hi:[0,1]
	v_pk_fma_f32 v[62:63], v[62:63], v[62:63], v[58:59] op_sel_hi:[1,1,0]
	v_pk_mul_f32 v[56:57], v[28:29], v[56:57] op_sel_hi:[1,0]
	v_mul_f32_e32 v58, v70, v70
	v_mul_f32_e32 v68, v56, v56
	v_mul_f32_e32 v62, v57, v57
	v_mul_f32_e32 v60, v71, v71
	v_pk_add_f32 v[56:57], v[68:69], v[62:63]
	v_pk_add_f32 v[58:59], v[58:59], v[60:61]
	v_pk_mul_f32 v[46:47], v[46:47], v[66:67] op_sel_hi:[1,0]
	v_pk_add_f32 v[56:57], v[56:57], v[58:59]
	v_pk_mul_f32 v[54:55], v[54:55], v[66:67] op_sel_hi:[1,0]
	v_add_f32_e32 v56, v56, v57
	ds_bpermute_b32 v57, v174, v56
	v_pk_mul_f32 v[54:55], v[136:137], v[54:55]
	s_mov_b64 s[0:1], 0x240000
	s_waitcnt lgkmcnt(0)
	v_add_f32_e32 v58, v56, v57
	ds_bpermute_b32 v59, v175, v58
	v_pk_mul_f32 v[56:57], v[132:133], v[46:47]
	v_pk_mul_f32 v[46:47], v[130:131], v[44:45]
	v_cvt_pk_bf16_f32 v44, v52, v53
	v_cvt_pk_bf16_f32 v45, v54, v55
	s_waitcnt lgkmcnt(0)
	v_add_f32_e32 v52, v58, v59
	v_fmamk_f32 v52, v52, 0x3c800000, v188
	v_mul_f32_e32 v53, 0x4b800000, v52
	v_cmp_gt_f32_e32 vcc, s92, v52
	v_cvt_pk_bf16_f32 v46, v46, v47
	v_cvt_pk_bf16_f32 v47, v56, v57
	global_store_dwordx4 v[64:65], v[44:47], off offset:64 sc1
	v_pk_mul_f32 v[54:55], v[12:13], v[160:161] op_sel_hi:[1,0]
	v_cndmask_b32_e32 v52, v52, v53, vcc
	v_rsq_f32_e32 v52, v52
	s_nop 0
	v_mul_f32_e32 v44, 0x45800000, v52
	v_cndmask_b32_e32 v46, v52, v44, vcc
	v_mul_f32_e32 v46, v163, v46
	v_pk_mul_f32 v[48:49], v[48:49], v[46:47] op_sel_hi:[1,0]
	v_lshl_add_u64 v[44:45], v[170:171], 0, s[0:1]
	v_pk_mul_f32 v[48:49], v[142:143], v[48:49]
	v_pk_mul_f32 v[40:41], v[40:41], v[46:47] op_sel_hi:[1,0]
	v_pk_mul_f32 v[42:43], v[42:43], v[46:47] op_sel_hi:[1,0]
	s_mov_b32 s0, 0x240000
	v_pk_mul_f32 v[50:51], v[50:51], v[46:47] op_sel_hi:[1,0]
	v_pk_mul_f32 v[52:53], v[140:141], v[42:43]
	v_pk_mul_f32 v[42:43], v[138:139], v[40:41]
	v_cvt_pk_bf16_f32 v40, v48, v49
	v_add_co_u32_e32 v48, vcc, s0, v170
	v_pk_mul_f32 v[50:51], v[144:145], v[50:51]
	s_nop 0
	v_addc_co_u32_e32 v49, vcc, 0, v171, vcc
	v_cvt_pk_bf16_f32 v41, v50, v51
	v_cvt_pk_bf16_f32 v42, v42, v43
	v_cvt_pk_bf16_f32 v43, v52, v53
	global_store_dwordx4 v[48:49], v[40:43], off sc1
	v_pk_mul_f32 v[52:53], v[14:15], v[160:161] op_sel_hi:[1,0]
	v_pk_mul_f32 v[36:37], v[36:37], v[46:47] op_sel_hi:[1,0]
	v_pk_mul_f32 v[40:41], v[34:35], v[160:161] op_sel_hi:[1,0]
	v_pk_mul_f32 v[42:43], v[32:33], v[160:161] op_sel_hi:[1,0]
	v_pk_mul_f32 v[40:41], v[40:41], v[40:41]
	v_pk_mul_f32 v[42:43], v[42:43], v[42:43]
	v_pk_mul_f32 v[36:37], v[134:135], v[36:37]
	v_pk_mov_b32 v[48:49], v[42:43], v[40:41] op_sel:[1,0]
	v_mov_b32_e32 v43, v41
	v_pk_add_f32 v[40:41], v[48:49], v[42:43]
	v_pk_mul_f32 v[42:43], v[26:27], v[160:161] op_sel_hi:[1,0]
	v_pk_mul_f32 v[48:49], v[24:25], v[160:161] op_sel_hi:[1,0]
	v_pk_mul_f32 v[42:43], v[42:43], v[42:43]
	v_pk_mul_f32 v[48:49], v[48:49], v[48:49]
	v_pk_add_f32 v[40:41], v[40:41], v[40:41] op_sel_hi:[0,1]
	v_pk_mov_b32 v[50:51], v[48:49], v[42:43] op_sel:[1,0]
	v_mov_b32_e32 v49, v43
	v_pk_add_f32 v[42:43], v[50:51], v[48:49]
	v_pk_mul_f32 v[50:51], v[20:21], v[160:161] op_sel_hi:[1,0]
	v_pk_mul_f32 v[48:49], v[22:23], v[160:161] op_sel_hi:[1,0]
	v_mul_f32_e32 v40, v50, v50
	v_pk_fma_f32 v[50:51], v[50:51], v[50:51], v[40:41] op_sel_hi:[1,1,0]
	v_mul_f32_e32 v40, v48, v48
	v_pk_add_f32 v[42:43], v[42:43], v[42:43] op_sel_hi:[0,1]
	v_pk_fma_f32 v[48:49], v[48:49], v[48:49], v[40:41] op_sel_hi:[1,1,0]
	v_mul_f32_e32 v50, v54, v54
	v_mul_f32_e32 v48, v55, v55
	v_mul_f32_e32 v40, v52, v52
	v_mul_f32_e32 v42, v53, v53
	v_pk_add_f32 v[48:49], v[50:51], v[48:49]
	v_pk_add_f32 v[40:41], v[40:41], v[42:43]
	v_pk_mul_f32 v[28:29], v[28:29], v[46:47] op_sel_hi:[1,0]
	v_pk_add_f32 v[40:41], v[48:49], v[40:41]
	v_pk_mul_f32 v[30:31], v[30:31], v[46:47] op_sel_hi:[1,0]
	v_add_f32_e32 v40, v40, v41
	ds_bpermute_b32 v41, v174, v40
	v_pk_mul_f32 v[38:39], v[38:39], v[46:47] op_sel_hi:[1,0]
	s_mov_b64 s[0:1], 0x280000
	v_pk_mul_f32 v[38:39], v[136:137], v[38:39]
	s_waitcnt lgkmcnt(0)
; __device__ __forceinline__ unsigned cvt_pk_bf16(float lo, float hi) { unsigned r; asm volatile("v_cvt_pk_bf16_f32 %0, %1, %2" : "=v"(r) : "v"(lo), "v"(hi)); return r; }
; #define GAS __attribute__((address_space(1)))
;     __device__ __forceinline__ void operator()(const pg8::f32x4 (&acc)[2][2][4][2], const pg8::Unit& u, int wr, int wc, int fr, int fq) const {
;     ...
;                 for (int m = 0; m < 4; ++m) { float ss = 0.f;
; #pragma unroll
;                     for (int bj = 0; bj < 2; ++bj)
; #pragma unroll
;                         for (int n = 0; n < 2; ++n) { const pg8::f32x4 v = acc[ai][bj][m][n] * rsr[ai][m]; ss += (v[0] * v[0] + v[1] * v[1]) + (v[2] * v[2] + v[3] * v[3]); }
;                     ss += __shfl_xor(ss, 16); ss += __shfl_xor(ss, 32);
;                     const float rs = rsqrtf(ss * (1.f / 64.f) + EPS);
;                     GAS pg8::bf16_t* rowp = O + (size_t)(row0 + ai * 128 + m * 16) * PW + ncol;
; #pragma unroll
;                     for (int bj = 0; bj < 2; ++bj) { const pg8::f32x4 v0 = acc[ai][bj][m][0] * (rs * rsr[ai][m]) * gv[bj][0], v1 = acc[ai][bj][m][1] * (rs * rsr[ai][m]) * gv[bj][1];
;                         pg8::u32x4 w; w.x = pg8::cvt_pk_bf16(v0[0], v0[1]); w.y = pg8::cvt_pk_bf16(v0[2], v0[3]); w.z = pg8::cvt_pk_bf16(v1[0], v1[1]); w.w = pg8::cvt_pk_bf16(v1[2], v1[3]);
;                         *(GAS pg8::u32x4*)(rowp + 32 * bj) = w; } }
	v_add_f32_e32 v42, v40, v41
	ds_bpermute_b32 v43, v175, v42
	v_pk_mul_f32 v[40:41], v[132:133], v[30:31]
	v_pk_mul_f32 v[30:31], v[130:131], v[28:29]
	v_cvt_pk_bf16_f32 v28, v36, v37
	v_cvt_pk_bf16_f32 v29, v38, v39
	s_waitcnt lgkmcnt(0)
	v_add_f32_e32 v36, v42, v43
	v_fmamk_f32 v36, v36, 0x3c800000, v188
	v_mul_f32_e32 v37, 0x4b800000, v36
	v_cmp_gt_f32_e32 vcc, s92, v36
	v_cvt_pk_bf16_f32 v30, v30, v31
	v_cvt_pk_bf16_f32 v31, v40, v41
	global_store_dwordx4 v[44:45], v[28:31], off offset:64 sc1
	s_nop 0
	v_cndmask_b32_e32 v36, v36, v37, vcc
	v_rsq_f32_e32 v36, v36
	s_nop 0
	v_mul_f32_e32 v28, 0x45800000, v36
	v_cndmask_b32_e32 v30, v36, v28, vcc
	v_mul_f32_e32 v30, v160, v30
	v_pk_mul_f32 v[32:33], v[32:33], v[30:31] op_sel_hi:[1,0]
	v_lshl_add_u64 v[28:29], v[170:171], 0, s[0:1]
	v_pk_mul_f32 v[32:33], v[142:143], v[32:33]
	v_pk_mul_f32 v[24:25], v[24:25], v[30:31] op_sel_hi:[1,0]
	v_pk_mul_f32 v[26:27], v[26:27], v[30:31] op_sel_hi:[1,0]
	s_mov_b32 s0, 0x280000
	v_pk_mul_f32 v[36:37], v[140:141], v[26:27]
	v_pk_mul_f32 v[26:27], v[138:139], v[24:25]
	v_cvt_pk_bf16_f32 v24, v32, v33
	v_add_co_u32_e32 v32, vcc, s0, v170
	v_pk_mul_f32 v[34:35], v[34:35], v[30:31] op_sel_hi:[1,0]
	s_nop 0
	v_addc_co_u32_e32 v33, vcc, 0, v171, vcc
	v_pk_mul_f32 v[34:35], v[144:145], v[34:35]
	v_pk_mul_f32 v[20:21], v[20:21], v[30:31] op_sel_hi:[1,0]
	v_cvt_pk_bf16_f32 v25, v34, v35
	v_cvt_pk_bf16_f32 v26, v26, v27
	v_cvt_pk_bf16_f32 v27, v36, v37
	global_store_dwordx4 v[32:33], v[24:27], off sc1
	v_pk_mul_f32 v[20:21], v[134:135], v[20:21]
	v_pk_mul_f32 v[12:13], v[12:13], v[30:31] op_sel_hi:[1,0]
	v_mov_b32_e32 v24, v161
	v_pk_mul_f32 v[26:27], v[18:19], v[24:25] op_sel_hi:[1,0]
	v_pk_mul_f32 v[32:33], v[16:17], v[24:25] op_sel_hi:[1,0]
	v_pk_mul_f32 v[26:27], v[26:27], v[26:27]
	v_pk_mul_f32 v[32:33], v[32:33], v[32:33]
	v_pk_mul_f32 v[38:39], v[2:3], v[24:25] op_sel_hi:[1,0]
	v_pk_mov_b32 v[34:35], v[32:33], v[26:27] op_sel:[1,0]
	v_mov_b32_e32 v33, v27
	v_pk_add_f32 v[26:27], v[34:35], v[32:33]
	v_pk_mul_f32 v[32:33], v[10:11], v[24:25] op_sel_hi:[1,0]
	v_pk_mul_f32 v[34:35], v[8:9], v[24:25] op_sel_hi:[1,0]
	v_pk_mul_f32 v[32:33], v[32:33], v[32:33]
	v_pk_mul_f32 v[34:35], v[34:35], v[34:35]
	v_pk_add_f32 v[26:27], v[26:27], v[26:27] op_sel_hi:[0,1]
	v_pk_mov_b32 v[36:37], v[34:35], v[32:33] op_sel:[1,0]
	v_mov_b32_e32 v35, v33
	v_pk_add_f32 v[32:33], v[36:37], v[34:35]
	v_pk_mul_f32 v[36:37], v[4:5], v[24:25] op_sel_hi:[1,0]
	v_pk_mul_f32 v[34:35], v[6:7], v[24:25] op_sel_hi:[1,0]
	v_mul_f32_e32 v26, v36, v36
	v_pk_fma_f32 v[36:37], v[36:37], v[36:37], v[26:27] op_sel_hi:[1,1,0]
	v_mul_f32_e32 v26, v34, v34
	v_pk_add_f32 v[32:33], v[32:33], v[32:33] op_sel_hi:[0,1]
	v_pk_fma_f32 v[34:35], v[34:35], v[34:35], v[26:27] op_sel_hi:[1,1,0]
	v_pk_mul_f32 v[24:25], v[0:1], v[24:25] op_sel_hi:[1,0]
	v_mul_f32_e32 v26, v38, v38
	v_mul_f32_e32 v36, v24, v24
	v_mul_f32_e32 v34, v25, v25
	v_mul_f32_e32 v32, v39, v39
	v_pk_add_f32 v[24:25], v[36:37], v[34:35]
	v_pk_add_f32 v[26:27], v[26:27], v[32:33]
	v_pk_mul_f32 v[14:15], v[14:15], v[30:31] op_sel_hi:[1,0]
	v_pk_add_f32 v[24:25], v[24:25], v[26:27]
	v_pk_mul_f32 v[22:23], v[22:23], v[30:31] op_sel_hi:[1,0]
	v_add_f32_e32 v24, v24, v25
	ds_bpermute_b32 v25, v174, v24
	v_pk_mul_f32 v[22:23], v[136:137], v[22:23]
	s_mov_b64 s[0:1], 0x2c0000
	s_waitcnt lgkmcnt(0)
	v_add_f32_e32 v26, v24, v25
	ds_bpermute_b32 v27, v175, v26
	v_pk_mul_f32 v[24:25], v[132:133], v[14:15]
	v_pk_mul_f32 v[14:15], v[130:131], v[12:13]
	v_cvt_pk_bf16_f32 v12, v20, v21
	v_cvt_pk_bf16_f32 v13, v22, v23
	s_waitcnt lgkmcnt(0)
	v_add_f32_e32 v20, v26, v27
	v_fmamk_f32 v20, v20, 0x3c800000, v188
	v_mul_f32_e32 v21, 0x4b800000, v20
	v_cmp_gt_f32_e32 vcc, s92, v20
	v_cvt_pk_bf16_f32 v14, v14, v15
	v_cvt_pk_bf16_f32 v15, v24, v25
	global_store_dwordx4 v[28:29], v[12:15], off offset:64 sc1
	s_nop 0
	v_cndmask_b32_e32 v20, v20, v21, vcc
	v_rsq_f32_e32 v20, v20
	s_nop 0
	v_mul_f32_e32 v12, 0x45800000, v20
	v_cndmask_b32_e32 v14, v20, v12, vcc
	v_mul_f32_e32 v14, v161, v14
	v_pk_mul_f32 v[16:17], v[16:17], v[14:15] op_sel_hi:[1,0]
	v_lshl_add_u64 v[12:13], v[170:171], 0, s[0:1]
	v_pk_mul_f32 v[16:17], v[142:143], v[16:17]
	v_pk_mul_f32 v[8:9], v[8:9], v[14:15] op_sel_hi:[1,0]
	v_pk_mul_f32 v[10:11], v[10:11], v[14:15] op_sel_hi:[1,0]
	s_mov_b32 s0, 0x2c0000
	v_pk_mul_f32 v[18:19], v[18:19], v[14:15] op_sel_hi:[1,0]
	v_pk_mul_f32 v[20:21], v[140:141], v[10:11]
	v_pk_mul_f32 v[10:11], v[138:139], v[8:9]
	v_cvt_pk_bf16_f32 v8, v16, v17
	v_add_co_u32_e32 v16, vcc, s0, v170
	v_pk_mul_f32 v[18:19], v[144:145], v[18:19]
	s_nop 0
	v_addc_co_u32_e32 v17, vcc, 0, v171, vcc
	v_cvt_pk_bf16_f32 v9, v18, v19
	v_pk_mul_f32 v[0:1], v[0:1], v[14:15] op_sel_hi:[1,0]
	v_pk_mul_f32 v[2:3], v[2:3], v[14:15] op_sel_hi:[1,0]
	v_cvt_pk_bf16_f32 v10, v10, v11
	v_cvt_pk_bf16_f32 v11, v20, v21
	global_store_dwordx4 v[16:17], v[8:11], off sc1
	v_pk_mul_f32 v[4:5], v[4:5], v[14:15] op_sel_hi:[1,0]
	v_pk_mul_f32 v[6:7], v[6:7], v[14:15] op_sel_hi:[1,0]
	v_pk_mul_f32 v[8:9], v[132:133], v[2:3]
	v_pk_mul_f32 v[2:3], v[130:131], v[0:1]
	v_pk_mul_f32 v[6:7], v[136:137], v[6:7]
	v_pk_mul_f32 v[4:5], v[134:135], v[4:5]
	s_nop 0
	v_cvt_pk_bf16_f32 v0, v4, v5
	v_cvt_pk_bf16_f32 v1, v6, v7
	v_cvt_pk_bf16_f32 v2, v2, v3
	v_cvt_pk_bf16_f32 v3, v8, v9
	global_store_dwordx4 v[12:13], v[0:3], off offset:64 sc1
	s_andn2_b64 vcc, exec, s[4:5]
	s_mov_b64 s[0:1], -1
	s_cbranch_vccnz .LBB0_74
